# speedup vs baseline: 1.0117x; 1.0117x over previous
; #define LAS __attribute__((address_space(3)))
; __device__ __forceinline__ unsigned cvt_pk_bf16(float lo, float hi) { const f32x2 v = {lo, hi}; const bf16v2 r = __builtin_convertvector(v, bf16v2); return __builtin_bit_cast(unsigned, r); }
; __device__ __forceinline__ float bf_lo(unsigned u) { return __uint_as_float(u << 16); }
; __device__ __forceinline__ float bf_hi(unsigned u) { return __uint_as_float(u & 0xffff0000u); }
; __device__ void ret_kv_phase(LAS unsigned char* lds, const bf16_t* PROJ, bf16_t* ST, const float* lgf, const float* lgb) {
;     ...
;         for (int sub = 0; sub < 4; ++sub) {
; #pragma unroll
;             for (int it = 0; it < 4; ++it) { const int idx = tid + 512 * it, row = idx >> 5, ch = idx & 31; const size_t tok = (size_t)c * 256 + sub * 64 + row;
;                 *(LAS u32x4*)(Kl + row * 528 + ch * 16) = *(const u32x4*)(PROJ + pj(tok, 4096 + h * 256 + ch * 8)); }
; #pragma unroll
;             for (int it = 0; it < 2; ++it) { const int idx = tid + 512 * it, row = idx >> 4, ch = idx & 15; const int jl = sub * 64 + row; const size_t tok = (size_t)c * 256 + jl;
;                 const float z = __expf(lg * (float)(dir ? jl : 255 - jl));
;                 const u32x4 v = *(const u32x4*)(PROJ + pj(tok, 5120 + h * 256 + dvh * 128 + ch * 8)); u32x4 w;
; #pragma unroll
;                 for (int e = 0; e < 4; ++e) w[e] = cvt_pk_bf16(bf_lo(v[e]) * z, bf_hi(v[e]) * z);
;                 *(LAS u32x4*)(Vl + row * 272 + ch * 16) = w; }
.LBB0_370:
	s_ashr_i32 s1, s14, 2
	s_and_b32 s0, s14, 4
	s_and_b32 s1, s1, -8
	s_or_b32 s4, s1, s0
	s_bfe_u32 s17, s14, 0x10004
	s_and_b32 s16, s14, 3
	s_cmp_eq_u32 s17, 0
	s_cselect_b64 vcc, -1, 0
	s_and_b64 s[0:1], vcc, exec
	s_cselect_b32 s0, s40, s42
	s_cselect_b32 s1, s41, s43
	s_add_u32 s0, s0, s2
	s_addc_u32 s1, s1, s3
	s_lshl_b32 s5, s16, 2
	s_ashr_i32 s4, s4, 2
	v_mov_b32_e32 v0, s5
	s_ashr_i32 s5, s4, 31
	s_mul_i32 s6, s16, 0x6000
	global_load_dword v94, v0, s[0:1]
	s_lshl_b64 s[0:1], s[4:5], 8
	s_add_i32 s5, s6, 0x18000
	s_add_u32 s12, s0, s5
	s_addc_u32 s13, s1, 0
	v_lshl_add_u64 v[176:177], s[12:13], 0, v[68:69]
	s_and_b32 s5, s15, 0x80
	s_add_i32 s6, s6, 0x30000
	v_lshlrev_b64 v[176:177], 9, v[176:177]
	s_add_u32 s6, s0, s6
	v_lshl_add_u64 v[176:177], v[66:67], 0, v[176:177]
	s_addc_u32 s7, s1, 0
	v_add_co_u32_e64 v176, s[0:1], s33, v176
	v_or_b32_e32 v0, s5, v96
	s_nop 0
	v_addc_co_u32_e64 v177, s[0:1], 0, v177, s[0:1]
	global_load_dwordx4 v[176:179], v[176:177], off
	v_lshlrev_b32_e32 v0, 1, v0
	v_lshl_add_u64 v[92:93], s[78:79], 0, v[0:1]
	v_cndmask_b32_e32 v0, v76, v98, vcc
	v_cvt_f32_i32_e32 v0, v0
	s_or_b32 s20, s12, 64
	s_mov_b32 s21, s13
	s_mulk_i32 s17, 0x60
	v_lshl_add_u64 v[180:181], s[12:13], 0, v[70:71]
	v_lshlrev_b64 v[180:181], 9, v[180:181]
	v_lshl_add_u64 v[180:181], v[66:67], 0, v[180:181]
	v_add_co_u32_e64 v180, s[0:1], s33, v180
	s_nop 1
	v_addc_co_u32_e64 v181, s[0:1], 0, v181, s[0:1]
	global_load_dwordx4 v[180:183], v[180:181], off
	v_lshl_add_u64 v[184:185], s[12:13], 0, v[72:73]
	v_lshlrev_b64 v[184:185], 9, v[184:185]
	v_lshl_add_u64 v[184:185], v[66:67], 0, v[184:185]
	v_add_co_u32_e64 v184, s[0:1], s33, v184
	s_nop 1
	v_addc_co_u32_e64 v185, s[0:1], 0, v185, s[0:1]
	global_load_dwordx4 v[184:187], v[184:185], off
	v_lshl_add_u64 v[188:189], s[12:13], 0, v[74:75]
	v_lshlrev_b64 v[188:189], 9, v[188:189]
	v_lshl_add_u64 v[188:189], v[66:67], 0, v[188:189]
	v_add_co_u32_e64 v188, s[0:1], s33, v188
	s_nop 1
	v_addc_co_u32_e64 v189, s[0:1], 0, v189, s[0:1]
	global_load_dwordx4 v[188:191], v[188:189], off
	v_lshl_add_u64 v[192:193], s[6:7], 0, v[76:77]
	v_lshlrev_b64 v[192:193], 9, v[192:193]
	v_lshl_add_u64 v[192:193], v[92:93], 0, v[192:193]
	v_add_co_u32_e64 v192, s[0:1], s33, v192
	s_nop 1
	v_addc_co_u32_e64 v193, s[0:1], 0, v193, s[0:1]
	global_load_dwordx4 v[192:195], v[192:193], off
	v_lshl_add_u64 v[196:197], s[6:7], 0, v[78:79]
	v_lshlrev_b64 v[196:197], 9, v[196:197]
	v_lshl_add_u64 v[196:197], v[92:93], 0, v[196:197]
	v_add_co_u32_e64 v196, s[0:1], s33, v196
	s_nop 1
	v_addc_co_u32_e64 v197, s[0:1], 0, v197, s[0:1]
	global_load_dwordx4 v[196:199], v[196:197], off
	s_waitcnt vmcnt(5)
	v_mul_f32_e32 v0, v94, v0
	v_mul_f32_e32 v0, 0x3fb8aa3b, v0
	v_exp_f32_e32 v0, v0
	s_waitcnt vmcnt(5)
	ds_write_b128 v107, v[176:179]
	s_nop 0
	s_nop 0
	s_nop 0
	s_nop 0
	s_nop 1
	s_nop 0
	s_nop 0
	s_waitcnt vmcnt(4)
	ds_write_b128 v108, v[180:183]
	s_nop 0
	s_nop 0
	s_nop 0
	s_nop 0
	s_nop 1
	s_nop 0
	s_nop 0
	s_waitcnt vmcnt(3)
	ds_write_b128 v109, v[184:187]
	s_nop 0
	s_nop 0
	s_nop 0
	s_nop 0
	s_nop 1
	s_nop 0
	s_nop 0
	s_waitcnt vmcnt(2)
	ds_write_b128 v110, v[188:191]
	s_nop 0
	s_nop 0
	s_nop 0
	s_nop 0
	s_nop 1
	s_nop 0
	s_nop 0
	s_waitcnt vmcnt(1)
	v_lshlrev_b32_e32 v6, 16, v192
	v_and_b32_e32 v7, 0xffff0000, v192
	v_pk_mul_f32 v[6:7], v[0:1], v[6:7] op_sel_hi:[0,1]
	v_cvt_pk_bf16_f32 v192, v6, v7
	v_lshlrev_b32_e32 v6, 16, v193
	v_and_b32_e32 v7, 0xffff0000, v193
	v_pk_mul_f32 v[6:7], v[0:1], v[6:7] op_sel_hi:[0,1]
	v_cvt_pk_bf16_f32 v193, v6, v7
	v_lshlrev_b32_e32 v6, 16, v194
	v_and_b32_e32 v7, 0xffff0000, v194
	v_pk_mul_f32 v[6:7], v[0:1], v[6:7] op_sel_hi:[0,1]
	v_cvt_pk_bf16_f32 v194, v6, v7
	v_lshlrev_b32_e32 v6, 16, v195
	v_and_b32_e32 v7, 0xffff0000, v195
	v_pk_mul_f32 v[6:7], v[0:1], v[6:7] op_sel_hi:[0,1]
	v_cvt_pk_bf16_f32 v195, v6, v7
	ds_write_b128 v111, v[192:195] offset:33792
	s_nop 0
	s_nop 0
	s_nop 0
	s_nop 0
	v_cndmask_b32_e32 v0, v78, v99, vcc
	s_nop 0
	s_nop 0
	s_nop 0
	v_cvt_f32_i32_e32 v0, v0
	v_mul_f32_e32 v0, v94, v0
	v_mul_f32_e32 v0, 0x3fb8aa3b, v0
	v_exp_f32_e32 v0, v0
	s_waitcnt vmcnt(0)
	v_lshlrev_b32_e32 v6, 16, v196
	v_and_b32_e32 v7, 0xffff0000, v196
	v_pk_mul_f32 v[6:7], v[0:1], v[6:7] op_sel_hi:[0,1]
	v_cvt_pk_bf16_f32 v196, v6, v7
	v_lshlrev_b32_e32 v6, 16, v197
	v_and_b32_e32 v7, 0xffff0000, v197
	v_pk_mul_f32 v[6:7], v[0:1], v[6:7] op_sel_hi:[0,1]
	v_cvt_pk_bf16_f32 v197, v6, v7
	v_lshlrev_b32_e32 v6, 16, v198
	v_and_b32_e32 v7, 0xffff0000, v198
	v_pk_mul_f32 v[6:7], v[0:1], v[6:7] op_sel_hi:[0,1]
	v_cvt_pk_bf16_f32 v198, v6, v7
	v_lshlrev_b32_e32 v6, 16, v199
	v_and_b32_e32 v7, 0xffff0000, v199
	v_pk_mul_f32 v[6:7], v[0:1], v[6:7] op_sel_hi:[0,1]
	v_cvt_pk_bf16_f32 v199, v6, v7
	ds_write_b128 v112, v[196:199] offset:33792
	s_waitcnt lgkmcnt(0)
	s_barrier
; #define LAS __attribute__((address_space(3)))
; __device__ __forceinline__ unsigned cvt_pk_bf16(float lo, float hi) { const f32x2 v = {lo, hi}; const bf16v2 r = __builtin_convertvector(v, bf16v2); return __builtin_bit_cast(unsigned, r); }
; __device__ __forceinline__ float bf_lo(unsigned u) { return __uint_as_float(u << 16); }
; __device__ __forceinline__ float bf_hi(unsigned u) { return __uint_as_float(u & 0xffff0000u); }
; #define MFMA16(a, b, c) __builtin_amdgcn_mfma_f32_16x16x32_bf16((a), (b), (c), 0, 0, 0)
; __device__ void ret_kv_phase(LAS unsigned char* lds, const bf16_t* PROJ, bf16_t* ST, const float* lgf, const float* lgb) {
;     ...
;             for (int it = 0; it < 4; ++it) { const int idx = tid + 512 * it, row = idx >> 5, ch = idx & 31; const size_t tok = (size_t)c * 256 + sub * 64 + row;
;                 *(LAS u32x4*)(Kl + row * 528 + ch * 16) = *(const u32x4*)(PROJ + pj(tok, 4096 + h * 256 + ch * 8)); }
; #pragma unroll
;             for (int it = 0; it < 2; ++it) { const int idx = tid + 512 * it, row = idx >> 4, ch = idx & 15; const int jl = sub * 64 + row; const size_t tok = (size_t)c * 256 + jl;
;                 const float z = __expf(lg * (float)(dir ? jl : 255 - jl));
;                 const u32x4 v = *(const u32x4*)(PROJ + pj(tok, 5120 + h * 256 + dvh * 128 + ch * 8)); u32x4 w;
; #pragma unroll
;                 for (int e = 0; e < 4; ++e) w[e] = cvt_pk_bf16(bf_lo(v[e]) * z, bf_hi(v[e]) * z);
;                 *(LAS u32x4*)(Vl + row * 272 + ch * 16) = w; }
;     ...
; #pragma unroll
;             for (int ks = 0; ks < 2; ++ks) {
;                 bf16x8 af[4], bfr[4];
;                 LAS unsigned char* vb = Vl + (32 * ks + 8 * g + q4) * 272 + (wr * 64) * 2 + 8 * p4;
;                 LAS unsigned char* kb = Kl + (32 * ks + 8 * g + q4) * 528 + (wc * 64) * 2 + 8 * p4;
; #pragma unroll
;                 for (int a = 0; a < 4; ++a) af[a] = tr_pair(vb + 32 * a, vb + 4 * 272 + 32 * a);
; #pragma unroll
;                 for (int bb = 0; bb < 4; ++bb) bfr[bb] = tr_pair(kb + 32 * bb, kb + 4 * 528 + 32 * bb);
; #pragma unroll
;                 for (int a = 0; a < 4; ++a)
; #pragma unroll
;                     for (int bb = 0; bb < 4; ++bb) acc[a][bb] = MFMA16(af[a], bfr[bb], acc[a][bb]);
;             }
	ds_read_b64_tr_b16 v[4:5], v113 offset:34880
	ds_read_b64_tr_b16 v[2:3], v113 offset:33792
	ds_read_b64_tr_b16 v[6:7], v113 offset:33824
	ds_read_b64_tr_b16 v[8:9], v113 offset:34912
	ds_read_b64_tr_b16 v[10:11], v113 offset:33856
	ds_read_b64_tr_b16 v[12:13], v113 offset:34944
	ds_read_b64_tr_b16 v[14:15], v113 offset:33888
	ds_read_b64_tr_b16 v[16:17], v113 offset:34976
	ds_read_b64_tr_b16 v[20:21], v114 offset:2112
	ds_read_b64_tr_b16 v[18:19], v114
	ds_read_b64_tr_b16 v[22:23], v114 offset:32
	ds_read_b64_tr_b16 v[24:25], v114 offset:2144
	ds_read_b64_tr_b16 v[26:27], v114 offset:64
	ds_read_b64_tr_b16 v[28:29], v114 offset:2176
	ds_read_b64_tr_b16 v[30:31], v114 offset:96
	ds_read_b64_tr_b16 v[32:33], v114 offset:2208
	s_waitcnt lgkmcnt(6)
	v_mfma_f32_16x16x32_bf16 v[34:37], v[2:5], v[18:21], 0
	v_cndmask_b32_e32 v0, v80, v100, vcc
	v_cvt_f32_i32_e32 v0, v0
	v_mul_f32_e32 v0, v94, v0
	v_mfma_f32_16x16x32_bf16 v[116:119], v[10:13], v[18:21], 0
	v_mul_f32_e32 v0, 0x3fb8aa3b, v0
	v_exp_f32_e32 v0, v0
	s_waitcnt lgkmcnt(4)
	v_mfma_f32_16x16x32_bf16 v[38:41], v[2:5], v[22:25], 0
	s_waitcnt lgkmcnt(2)
	v_mfma_f32_16x16x32_bf16 v[42:45], v[2:5], v[26:29], 0
	s_waitcnt lgkmcnt(0)
	v_mfma_f32_16x16x32_bf16 v[46:49], v[2:5], v[30:33], 0
	v_mfma_f32_16x16x32_bf16 v[62:65], v[6:9], v[30:33], 0
	v_mfma_f32_16x16x32_bf16 v[128:131], v[10:13], v[30:33], 0
	v_mfma_f32_16x16x32_bf16 v[132:135], v[14:17], v[18:21], 0
	v_mfma_f32_16x16x32_bf16 v[136:139], v[14:17], v[22:25], 0
	v_mfma_f32_16x16x32_bf16 v[140:143], v[14:17], v[26:29], 0
	v_mfma_f32_16x16x32_bf16 v[144:147], v[14:17], v[30:33], 0
	ds_read_b64_tr_b16 v[14:15], v113 offset:42496
	ds_read_b64_tr_b16 v[16:17], v113 offset:43584
	ds_read_b64_tr_b16 v[30:31], v113 offset:42528
	ds_read_b64_tr_b16 v[32:33], v113 offset:43616
	ds_read_b64_tr_b16 v[148:149], v113 offset:42560
	ds_read_b64_tr_b16 v[150:151], v113 offset:43648
	ds_read_b64_tr_b16 v[152:153], v113 offset:42592
	ds_read_b64_tr_b16 v[154:155], v113 offset:43680
	ds_read_b64_tr_b16 v[156:157], v114 offset:16896
	ds_read_b64_tr_b16 v[158:159], v114 offset:19008
	ds_read_b64_tr_b16 v[160:161], v114 offset:16928
	ds_read_b64_tr_b16 v[162:163], v114 offset:19040
	ds_read_b64_tr_b16 v[164:165], v114 offset:16960
	ds_read_b64_tr_b16 v[166:167], v114 offset:19072
	ds_read_b64_tr_b16 v[168:169], v114 offset:16992
	ds_read_b64_tr_b16 v[170:171], v114 offset:19104
	s_waitcnt lgkmcnt(0)
	s_barrier
	v_mfma_f32_16x16x32_bf16 v[2:5], v[14:17], v[156:159], v[34:37]
	v_mfma_f32_16x16x32_bf16 v[34:37], v[148:151], v[156:159], v[116:119]
	s_nop 2
	v_lshl_add_u64 v[176:177], s[20:21], 0, v[68:69]
	v_lshlrev_b64 v[176:177], 9, v[176:177]
	v_lshl_add_u64 v[176:177], v[66:67], 0, v[176:177]
	v_add_co_u32_e64 v176, s[0:1], s33, v176
	v_mfma_f32_16x16x32_bf16 v[120:123], v[10:13], v[22:25], 0
	s_nop 0
	v_addc_co_u32_e64 v177, s[0:1], 0, v177, s[0:1]
	global_load_dwordx4 v[176:179], v[176:177], off
	v_mfma_f32_16x16x32_bf16 v[50:53], v[6:9], v[18:21], 0
	v_lshl_add_u64 v[180:181], s[20:21], 0, v[70:71]
	v_lshlrev_b64 v[180:181], 9, v[180:181]
	v_lshl_add_u64 v[180:181], v[66:67], 0, v[180:181]
	v_add_co_u32_e64 v180, s[0:1], s33, v180
	s_nop 1
	v_addc_co_u32_e64 v181, s[0:1], 0, v181, s[0:1]
	global_load_dwordx4 v[180:183], v[180:181], off
	v_lshl_add_u64 v[184:185], s[20:21], 0, v[72:73]
	v_lshlrev_b64 v[184:185], 9, v[184:185]
	v_lshl_add_u64 v[184:185], v[66:67], 0, v[184:185]
	v_add_co_u32_e64 v184, s[0:1], s33, v184
	s_nop 1
	v_addc_co_u32_e64 v185, s[0:1], 0, v185, s[0:1]
	global_load_dwordx4 v[184:187], v[184:185], off
	v_lshl_add_u64 v[188:189], s[20:21], 0, v[74:75]
	v_lshlrev_b64 v[188:189], 9, v[188:189]
	v_lshl_add_u64 v[188:189], v[66:67], 0, v[188:189]
	v_add_co_u32_e64 v188, s[0:1], s33, v188
	s_nop 1
	v_addc_co_u32_e64 v189, s[0:1], 0, v189, s[0:1]
	global_load_dwordx4 v[188:191], v[188:189], off
	v_lshl_add_u64 v[192:193], s[6:7], 0, v[80:81]
	v_lshlrev_b64 v[192:193], 9, v[192:193]
	v_lshl_add_u64 v[192:193], v[92:93], 0, v[192:193]
	v_add_co_u32_e64 v192, s[0:1], s33, v192
	s_nop 1
	v_addc_co_u32_e64 v193, s[0:1], 0, v193, s[0:1]
	global_load_dwordx4 v[192:195], v[192:193], off
	v_lshl_add_u64 v[196:197], s[6:7], 0, v[82:83]
	v_lshlrev_b64 v[196:197], 9, v[196:197]
	v_lshl_add_u64 v[196:197], v[92:93], 0, v[196:197]
	v_add_co_u32_e64 v196, s[0:1], s33, v196
	s_nop 1
	v_addc_co_u32_e64 v197, s[0:1], 0, v197, s[0:1]
	global_load_dwordx4 v[196:199], v[196:197], off
	s_waitcnt vmcnt(5)
	ds_write_b128 v107, v[176:179]
	s_nop 0
	s_nop 0
	s_nop 0
	s_nop 0
	v_mfma_f32_16x16x32_bf16 v[54:57], v[6:9], v[22:25], 0
	s_nop 0
	s_nop 0
	s_nop 0
	v_mfma_f32_16x16x32_bf16 v[58:61], v[6:9], v[26:29], 0
	s_waitcnt vmcnt(4)
	ds_write_b128 v108, v[180:183]
	s_nop 0
	s_nop 0
	s_nop 0
	s_nop 0
	v_mfma_f32_16x16x32_bf16 v[6:9], v[14:17], v[160:163], v[38:41]
	s_nop 0
	s_nop 0
	s_nop 0
	v_mfma_f32_16x16x32_bf16 v[38:41], v[148:151], v[160:163], v[120:123]
	s_waitcnt vmcnt(3)
	ds_write_b128 v109, v[184:187]
	s_nop 0
	s_nop 0
	s_nop 0
	s_nop 0
	v_mfma_f32_16x16x32_bf16 v[124:127], v[10:13], v[26:29], 0
	s_nop 0
	s_nop 0
	s_nop 0
	v_mfma_f32_16x16x32_bf16 v[10:13], v[14:17], v[164:167], v[42:45]
	s_or_b32 s20, s12, 0x80
	s_or_b32 s12, s12, 0xc0
	s_waitcnt vmcnt(2)
	ds_write_b128 v110, v[188:191]
	s_nop 0
	s_nop 0
	s_nop 0
	s_nop 0
	v_mfma_f32_16x16x32_bf16 v[14:17], v[14:17], v[168:171], v[46:49]
	s_nop 0
	s_nop 0
	s_nop 0
	v_mfma_f32_16x16x32_bf16 v[18:21], v[30:33], v[156:159], v[50:53]
	s_waitcnt vmcnt(1)
; #define LAS __attribute__((address_space(3)))
; __device__ __forceinline__ unsigned cvt_pk_bf16(float lo, float hi) { const f32x2 v = {lo, hi}; const bf16v2 r = __builtin_convertvector(v, bf16v2); return __builtin_bit_cast(unsigned, r); }
; __device__ __forceinline__ float bf_lo(unsigned u) { return __uint_as_float(u << 16); }
; __device__ __forceinline__ float bf_hi(unsigned u) { return __uint_as_float(u & 0xffff0000u); }
; #define MFMA16(a, b, c) __builtin_amdgcn_mfma_f32_16x16x32_bf16((a), (b), (c), 0, 0, 0)
; __device__ void ret_kv_phase(LAS unsigned char* lds, const bf16_t* PROJ, bf16_t* ST, const float* lgf, const float* lgb) {
;     ...
;             for (int it = 0; it < 2; ++it) { const int idx = tid + 512 * it, row = idx >> 4, ch = idx & 15; const int jl = sub * 64 + row; const size_t tok = (size_t)c * 256 + jl;
;                 const float z = __expf(lg * (float)(dir ? jl : 255 - jl));
;                 const u32x4 v = *(const u32x4*)(PROJ + pj(tok, 5120 + h * 256 + dvh * 128 + ch * 8)); u32x4 w;
; #pragma unroll
;                 for (int e = 0; e < 4; ++e) w[e] = cvt_pk_bf16(bf_lo(v[e]) * z, bf_hi(v[e]) * z);
;                 *(LAS u32x4*)(Vl + row * 272 + ch * 16) = w; }
;             __syncthreads();
; #pragma unroll
;             for (int ks = 0; ks < 2; ++ks) {
;                 bf16x8 af[4], bfr[4];
;                 LAS unsigned char* vb = Vl + (32 * ks + 8 * g + q4) * 272 + (wr * 64) * 2 + 8 * p4;
;                 LAS unsigned char* kb = Kl + (32 * ks + 8 * g + q4) * 528 + (wc * 64) * 2 + 8 * p4;
; #pragma unroll
;                 for (int a = 0; a < 4; ++a) af[a] = tr_pair(vb + 32 * a, vb + 4 * 272 + 32 * a);
; #pragma unroll
;                 for (int bb = 0; bb < 4; ++bb) bfr[bb] = tr_pair(kb + 32 * bb, kb + 4 * 528 + 32 * bb);
; #pragma unroll
;                 for (int a = 0; a < 4; ++a)
; #pragma unroll
;                     for (int bb = 0; bb < 4; ++bb) acc[a][bb] = MFMA16(af[a], bfr[bb], acc[a][bb]);
;             }
	v_lshlrev_b32_e32 v120, 16, v192
	v_and_b32_e32 v121, 0xffff0000, v192
	v_pk_mul_f32 v[120:121], v[0:1], v[120:121] op_sel_hi:[0,1]
	v_cvt_pk_bf16_f32 v192, v120, v121
	v_lshlrev_b32_e32 v120, 16, v193
	v_and_b32_e32 v121, 0xffff0000, v193
	v_pk_mul_f32 v[120:121], v[0:1], v[120:121] op_sel_hi:[0,1]
	v_cvt_pk_bf16_f32 v193, v120, v121
	v_lshlrev_b32_e32 v120, 16, v194
	v_and_b32_e32 v121, 0xffff0000, v194
	v_pk_mul_f32 v[120:121], v[0:1], v[120:121] op_sel_hi:[0,1]
	v_cvt_pk_bf16_f32 v194, v120, v121
	v_lshlrev_b32_e32 v120, 16, v195
	v_and_b32_e32 v121, 0xffff0000, v195
	v_pk_mul_f32 v[120:121], v[0:1], v[120:121] op_sel_hi:[0,1]
	v_cvt_pk_bf16_f32 v195, v120, v121
	ds_write_b128 v111, v[192:195] offset:33792
	s_nop 0
	s_nop 0
	s_nop 0
	s_nop 0
	v_cndmask_b32_e32 v0, v82, v101, vcc
	s_nop 0
	s_nop 0
	s_nop 0
	v_cvt_f32_i32_e32 v0, v0
	v_mfma_f32_16x16x32_bf16 v[22:25], v[30:33], v[160:163], v[54:57]
	v_mul_f32_e32 v0, v94, v0
	v_mul_f32_e32 v0, 0x3fb8aa3b, v0
	v_exp_f32_e32 v0, v0
	v_mfma_f32_16x16x32_bf16 v[26:29], v[30:33], v[164:167], v[58:61]
	s_waitcnt vmcnt(0)
	v_lshlrev_b32_e32 v120, 16, v196
	v_and_b32_e32 v121, 0xffff0000, v196
	v_pk_mul_f32 v[120:121], v[0:1], v[120:121] op_sel_hi:[0,1]
	v_cvt_pk_bf16_f32 v196, v120, v121
	v_lshlrev_b32_e32 v120, 16, v197
	v_and_b32_e32 v121, 0xffff0000, v197
	v_pk_mul_f32 v[120:121], v[0:1], v[120:121] op_sel_hi:[0,1]
	v_cvt_pk_bf16_f32 v197, v120, v121
	v_lshlrev_b32_e32 v120, 16, v198
	v_and_b32_e32 v121, 0xffff0000, v198
	v_pk_mul_f32 v[120:121], v[0:1], v[120:121] op_sel_hi:[0,1]
	v_cvt_pk_bf16_f32 v198, v120, v121
	v_lshlrev_b32_e32 v120, 16, v199
	v_and_b32_e32 v121, 0xffff0000, v199
	v_pk_mul_f32 v[120:121], v[0:1], v[120:121] op_sel_hi:[0,1]
	v_cvt_pk_bf16_f32 v199, v120, v121
	v_mfma_f32_16x16x32_bf16 v[30:33], v[30:33], v[168:171], v[62:65]
	ds_write_b128 v112, v[196:199] offset:33792
	s_waitcnt lgkmcnt(0)
	s_barrier
	v_mfma_f32_16x16x32_bf16 v[42:45], v[148:151], v[164:167], v[124:127]
	v_cndmask_b32_e32 v0, v84, v102, vcc
	v_cvt_f32_i32_e32 v0, v0
	v_mfma_f32_16x16x32_bf16 v[46:49], v[148:151], v[168:171], v[128:131]
	v_mul_f32_e32 v0, v94, v0
	v_mfma_f32_16x16x32_bf16 v[50:53], v[152:155], v[156:159], v[132:135]
	v_mul_f32_e32 v0, 0x3fb8aa3b, v0
	v_exp_f32_e32 v0, v0
	v_mfma_f32_16x16x32_bf16 v[54:57], v[152:155], v[160:163], v[136:139]
	v_mfma_f32_16x16x32_bf16 v[58:61], v[152:155], v[164:167], v[140:143]
	v_mfma_f32_16x16x32_bf16 v[62:65], v[152:155], v[168:171], v[144:147]
	ds_read_b64_tr_b16 v[118:119], v113 offset:34880
	ds_read_b64_tr_b16 v[116:117], v113 offset:33792
	ds_read_b64_tr_b16 v[120:121], v113 offset:33824
	ds_read_b64_tr_b16 v[122:123], v113 offset:34912
	ds_read_b64_tr_b16 v[124:125], v113 offset:33856
	ds_read_b64_tr_b16 v[126:127], v113 offset:34944
	ds_read_b64_tr_b16 v[128:129], v113 offset:33888
	ds_read_b64_tr_b16 v[130:131], v113 offset:34976
	ds_read_b64_tr_b16 v[134:135], v114 offset:2112
	ds_read_b64_tr_b16 v[132:133], v114
	ds_read_b64_tr_b16 v[136:137], v114 offset:32
	ds_read_b64_tr_b16 v[138:139], v114 offset:2144
	ds_read_b64_tr_b16 v[140:141], v114 offset:64
	ds_read_b64_tr_b16 v[142:143], v114 offset:2176
	ds_read_b64_tr_b16 v[144:145], v114 offset:96
	ds_read_b64_tr_b16 v[146:147], v114 offset:2208
	s_waitcnt lgkmcnt(6)
	v_mfma_f32_16x16x32_bf16 v[2:5], v[116:119], v[132:135], v[2:5]
	s_waitcnt lgkmcnt(4)
	v_mfma_f32_16x16x32_bf16 v[6:9], v[116:119], v[136:139], v[6:9]
	s_waitcnt lgkmcnt(2)
	v_mfma_f32_16x16x32_bf16 v[10:13], v[116:119], v[140:143], v[10:13]
	s_waitcnt lgkmcnt(0)
	v_mfma_f32_16x16x32_bf16 v[14:17], v[116:119], v[144:147], v[14:17]
	v_mfma_f32_16x16x32_bf16 v[18:21], v[120:123], v[132:135], v[18:21]
	v_mfma_f32_16x16x32_bf16 v[22:25], v[120:123], v[136:139], v[22:25]
	v_mfma_f32_16x16x32_bf16 v[26:29], v[120:123], v[140:143], v[26:29]
	v_mfma_f32_16x16x32_bf16 v[30:33], v[120:123], v[144:147], v[30:33]
	v_mfma_f32_16x16x32_bf16 v[34:37], v[124:127], v[132:135], v[34:37]
	v_mfma_f32_16x16x32_bf16 v[38:41], v[124:127], v[136:139], v[38:41]
	v_mfma_f32_16x16x32_bf16 v[42:45], v[124:127], v[140:143], v[42:45]
	v_mfma_f32_16x16x32_bf16 v[46:49], v[124:127], v[144:147], v[46:49]
	v_mfma_f32_16x16x32_bf16 v[50:53], v[128:131], v[132:135], v[50:53]
	v_mfma_f32_16x16x32_bf16 v[54:57], v[128:131], v[136:139], v[54:57]
	v_mfma_f32_16x16x32_bf16 v[58:61], v[128:131], v[140:143], v[58:61]
	v_mfma_f32_16x16x32_bf16 v[62:65], v[128:131], v[144:147], v[62:65]
	ds_read_b64_tr_b16 v[116:117], v113 offset:42496
	ds_read_b64_tr_b16 v[118:119], v113 offset:43584
	ds_read_b64_tr_b16 v[120:121], v113 offset:42528
	ds_read_b64_tr_b16 v[122:123], v113 offset:43616
	ds_read_b64_tr_b16 v[124:125], v113 offset:42560
	ds_read_b64_tr_b16 v[126:127], v113 offset:43648
	ds_read_b64_tr_b16 v[128:129], v113 offset:42592
	ds_read_b64_tr_b16 v[130:131], v113 offset:43680
	ds_read_b64_tr_b16 v[132:133], v114 offset:16896
	ds_read_b64_tr_b16 v[134:135], v114 offset:19008
	ds_read_b64_tr_b16 v[136:137], v114 offset:16928
	ds_read_b64_tr_b16 v[138:139], v114 offset:19040
	ds_read_b64_tr_b16 v[140:141], v114 offset:16960
	ds_read_b64_tr_b16 v[142:143], v114 offset:19072
	ds_read_b64_tr_b16 v[144:145], v114 offset:16992
	ds_read_b64_tr_b16 v[146:147], v114 offset:19104
	s_waitcnt lgkmcnt(0)
	s_barrier
; #define LAS __attribute__((address_space(3)))
; __device__ __forceinline__ unsigned cvt_pk_bf16(float lo, float hi) { const f32x2 v = {lo, hi}; const bf16v2 r = __builtin_convertvector(v, bf16v2); return __builtin_bit_cast(unsigned, r); }
; __device__ __forceinline__ float bf_lo(unsigned u) { return __uint_as_float(u << 16); }
; __device__ __forceinline__ float bf_hi(unsigned u) { return __uint_as_float(u & 0xffff0000u); }
; #define MFMA16(a, b, c) __builtin_amdgcn_mfma_f32_16x16x32_bf16((a), (b), (c), 0, 0, 0)
; __device__ void ret_kv_phase(LAS unsigned char* lds, const bf16_t* PROJ, bf16_t* ST, const float* lgf, const float* lgb) {
;     ...
;             for (int it = 0; it < 4; ++it) { const int idx = tid + 512 * it, row = idx >> 5, ch = idx & 31; const size_t tok = (size_t)c * 256 + sub * 64 + row;
;                 *(LAS u32x4*)(Kl + row * 528 + ch * 16) = *(const u32x4*)(PROJ + pj(tok, 4096 + h * 256 + ch * 8)); }
; #pragma unroll
;             for (int it = 0; it < 2; ++it) { const int idx = tid + 512 * it, row = idx >> 4, ch = idx & 15; const int jl = sub * 64 + row; const size_t tok = (size_t)c * 256 + jl;
;                 const float z = __expf(lg * (float)(dir ? jl : 255 - jl));
;                 const u32x4 v = *(const u32x4*)(PROJ + pj(tok, 5120 + h * 256 + dvh * 128 + ch * 8)); u32x4 w;
; #pragma unroll
;                 for (int e = 0; e < 4; ++e) w[e] = cvt_pk_bf16(bf_lo(v[e]) * z, bf_hi(v[e]) * z);
;                 *(LAS u32x4*)(Vl + row * 272 + ch * 16) = w; }
;     ...
; #pragma unroll
;             for (int ks = 0; ks < 2; ++ks) {
;                 bf16x8 af[4], bfr[4];
;                 LAS unsigned char* vb = Vl + (32 * ks + 8 * g + q4) * 272 + (wr * 64) * 2 + 8 * p4;
;                 LAS unsigned char* kb = Kl + (32 * ks + 8 * g + q4) * 528 + (wc * 64) * 2 + 8 * p4;
; #pragma unroll
;                 for (int a = 0; a < 4; ++a) af[a] = tr_pair(vb + 32 * a, vb + 4 * 272 + 32 * a);
; #pragma unroll
;                 for (int bb = 0; bb < 4; ++bb) bfr[bb] = tr_pair(kb + 32 * bb, kb + 4 * 528 + 32 * bb);
; #pragma unroll
;                 for (int a = 0; a < 4; ++a)
; #pragma unroll
;                     for (int bb = 0; bb < 4; ++bb) acc[a][bb] = MFMA16(af[a], bfr[bb], acc[a][bb]);
	v_mfma_f32_16x16x32_bf16 v[2:5], v[116:119], v[132:135], v[2:5]
	v_mfma_f32_16x16x32_bf16 v[6:9], v[116:119], v[136:139], v[6:9]
	v_mfma_f32_16x16x32_bf16 v[10:13], v[116:119], v[140:143], v[10:13]
	v_mfma_f32_16x16x32_bf16 v[14:17], v[116:119], v[144:147], v[14:17]
	v_lshl_add_u64 v[176:177], s[20:21], 0, v[68:69]
	v_lshlrev_b64 v[176:177], 9, v[176:177]
	v_lshl_add_u64 v[176:177], v[66:67], 0, v[176:177]
	v_add_co_u32_e64 v176, s[0:1], s33, v176
	v_mfma_f32_16x16x32_bf16 v[18:21], v[120:123], v[132:135], v[18:21]
	s_nop 0
	v_addc_co_u32_e64 v177, s[0:1], 0, v177, s[0:1]
	global_load_dwordx4 v[176:179], v[176:177], off
	v_mfma_f32_16x16x32_bf16 v[22:25], v[120:123], v[136:139], v[22:25]
	v_lshl_add_u64 v[180:181], s[20:21], 0, v[70:71]
	v_lshlrev_b64 v[180:181], 9, v[180:181]
	v_lshl_add_u64 v[180:181], v[66:67], 0, v[180:181]
	v_add_co_u32_e64 v180, s[0:1], s33, v180
	s_nop 1
	v_addc_co_u32_e64 v181, s[0:1], 0, v181, s[0:1]
	global_load_dwordx4 v[180:183], v[180:181], off
	v_lshl_add_u64 v[184:185], s[20:21], 0, v[72:73]
	v_lshlrev_b64 v[184:185], 9, v[184:185]
	v_lshl_add_u64 v[184:185], v[66:67], 0, v[184:185]
	v_add_co_u32_e64 v184, s[0:1], s33, v184
	s_nop 1
	v_addc_co_u32_e64 v185, s[0:1], 0, v185, s[0:1]
	global_load_dwordx4 v[184:187], v[184:185], off
	v_lshl_add_u64 v[188:189], s[20:21], 0, v[74:75]
	v_lshlrev_b64 v[188:189], 9, v[188:189]
	v_lshl_add_u64 v[188:189], v[66:67], 0, v[188:189]
	v_add_co_u32_e64 v188, s[0:1], s33, v188
	s_nop 1
	v_addc_co_u32_e64 v189, s[0:1], 0, v189, s[0:1]
	global_load_dwordx4 v[188:191], v[188:189], off
	v_lshl_add_u64 v[192:193], s[6:7], 0, v[84:85]
	v_lshlrev_b64 v[192:193], 9, v[192:193]
	v_lshl_add_u64 v[192:193], v[92:93], 0, v[192:193]
	v_add_co_u32_e64 v192, s[0:1], s33, v192
	s_nop 1
	v_addc_co_u32_e64 v193, s[0:1], 0, v193, s[0:1]
	global_load_dwordx4 v[192:195], v[192:193], off
	v_lshl_add_u64 v[196:197], s[6:7], 0, v[86:87]
	v_lshlrev_b64 v[196:197], 9, v[196:197]
	v_lshl_add_u64 v[196:197], v[92:93], 0, v[196:197]
	v_add_co_u32_e64 v196, s[0:1], s33, v196
	s_nop 1
	v_addc_co_u32_e64 v197, s[0:1], 0, v197, s[0:1]
	global_load_dwordx4 v[196:199], v[196:197], off
	s_waitcnt vmcnt(5)
	ds_write_b128 v107, v[176:179]
	s_nop 0
	s_nop 0
	s_nop 0
	s_nop 0
	v_mfma_f32_16x16x32_bf16 v[26:29], v[120:123], v[140:143], v[26:29]
	s_nop 0
	s_nop 0
	s_nop 0
	v_mfma_f32_16x16x32_bf16 v[30:33], v[120:123], v[144:147], v[30:33]
	s_waitcnt vmcnt(4)
	ds_write_b128 v108, v[180:183]
	s_nop 0
	s_nop 0
	s_nop 0
	s_nop 0
	v_mfma_f32_16x16x32_bf16 v[34:37], v[124:127], v[132:135], v[34:37]
	s_nop 0
	s_nop 0
	s_nop 0
	v_mfma_f32_16x16x32_bf16 v[38:41], v[124:127], v[136:139], v[38:41]
	s_waitcnt vmcnt(3)
	ds_write_b128 v109, v[184:187]
	s_nop 0
	s_nop 0
	s_nop 0
	s_nop 0
	v_mfma_f32_16x16x32_bf16 v[42:45], v[124:127], v[140:143], v[42:45]
	s_nop 0
	s_nop 0
	s_nop 0
	v_mfma_f32_16x16x32_bf16 v[46:49], v[124:127], v[144:147], v[46:49]
	s_waitcnt vmcnt(2)
	ds_write_b128 v110, v[188:191]
	s_nop 0
	s_nop 0
	s_nop 0
	s_nop 0
	v_mfma_f32_16x16x32_bf16 v[50:53], v[128:131], v[132:135], v[50:53]
	s_nop 0
	s_nop 0
	s_nop 0
	v_mfma_f32_16x16x32_bf16 v[54:57], v[128:131], v[136:139], v[54:57]
	s_waitcnt vmcnt(1)
	v_lshlrev_b32_e32 v120, 16, v192
	v_and_b32_e32 v121, 0xffff0000, v192
	v_pk_mul_f32 v[120:121], v[0:1], v[120:121] op_sel_hi:[0,1]
	v_cvt_pk_bf16_f32 v192, v120, v121
	v_lshlrev_b32_e32 v120, 16, v193
	v_and_b32_e32 v121, 0xffff0000, v193
	v_pk_mul_f32 v[120:121], v[0:1], v[120:121] op_sel_hi:[0,1]
	v_cvt_pk_bf16_f32 v193, v120, v121
	v_lshlrev_b32_e32 v120, 16, v194
	v_and_b32_e32 v121, 0xffff0000, v194
	v_pk_mul_f32 v[120:121], v[0:1], v[120:121] op_sel_hi:[0,1]
	v_cvt_pk_bf16_f32 v194, v120, v121
	v_lshlrev_b32_e32 v120, 16, v195
	v_and_b32_e32 v121, 0xffff0000, v195
	v_pk_mul_f32 v[120:121], v[0:1], v[120:121] op_sel_hi:[0,1]
	v_cvt_pk_bf16_f32 v195, v120, v121
	ds_write_b128 v111, v[192:195] offset:33792
	s_nop 0
	s_nop 0
	s_nop 0
	s_nop 0
	v_cndmask_b32_e32 v0, v86, v103, vcc
	s_nop 0
	s_nop 0
	s_nop 0
	v_cvt_f32_i32_e32 v0, v0
	v_mfma_f32_16x16x32_bf16 v[58:61], v[128:131], v[140:143], v[58:61]
	v_mul_f32_e32 v0, v94, v0
	v_mul_f32_e32 v0, 0x3fb8aa3b, v0
	v_exp_f32_e32 v0, v0
	v_mfma_f32_16x16x32_bf16 v[62:65], v[128:131], v[144:147], v[62:65]
	s_waitcnt vmcnt(0)
	v_lshlrev_b32_e32 v120, 16, v196
	v_and_b32_e32 v121, 0xffff0000, v196
	v_pk_mul_f32 v[120:121], v[0:1], v[120:121] op_sel_hi:[0,1]
	v_cvt_pk_bf16_f32 v196, v120, v121
	v_lshlrev_b32_e32 v120, 16, v197
	v_and_b32_e32 v121, 0xffff0000, v197
	v_pk_mul_f32 v[120:121], v[0:1], v[120:121] op_sel_hi:[0,1]
	v_cvt_pk_bf16_f32 v197, v120, v121
	v_lshlrev_b32_e32 v120, 16, v198
	v_and_b32_e32 v121, 0xffff0000, v198
	v_pk_mul_f32 v[120:121], v[0:1], v[120:121] op_sel_hi:[0,1]
	v_cvt_pk_bf16_f32 v198, v120, v121
	v_lshlrev_b32_e32 v120, 16, v199
	v_and_b32_e32 v121, 0xffff0000, v199
	v_pk_mul_f32 v[120:121], v[0:1], v[120:121] op_sel_hi:[0,1]
	v_cvt_pk_bf16_f32 v199, v120, v121
	ds_write_b128 v112, v[196:199] offset:33792
	s_waitcnt lgkmcnt(0)
	s_barrier
; #define LAS __attribute__((address_space(3)))
; __device__ __forceinline__ unsigned cvt_pk_bf16(float lo, float hi) { const f32x2 v = {lo, hi}; const bf16v2 r = __builtin_convertvector(v, bf16v2); return __builtin_bit_cast(unsigned, r); }
; __device__ __forceinline__ float bf_lo(unsigned u) { return __uint_as_float(u << 16); }
; __device__ __forceinline__ float bf_hi(unsigned u) { return __uint_as_float(u & 0xffff0000u); }
; #define MFMA16(a, b, c) __builtin_amdgcn_mfma_f32_16x16x32_bf16((a), (b), (c), 0, 0, 0)
; __device__ void ret_kv_phase(LAS unsigned char* lds, const bf16_t* PROJ, bf16_t* ST, const float* lgf, const float* lgb) {
;     ...
;             for (int it = 0; it < 4; ++it) { const int idx = tid + 512 * it, row = idx >> 5, ch = idx & 31; const size_t tok = (size_t)c * 256 + sub * 64 + row;
;                 *(LAS u32x4*)(Kl + row * 528 + ch * 16) = *(const u32x4*)(PROJ + pj(tok, 4096 + h * 256 + ch * 8)); }
; #pragma unroll
;             for (int it = 0; it < 2; ++it) { const int idx = tid + 512 * it, row = idx >> 4, ch = idx & 15; const int jl = sub * 64 + row; const size_t tok = (size_t)c * 256 + jl;
;                 const float z = __expf(lg * (float)(dir ? jl : 255 - jl));
;                 const u32x4 v = *(const u32x4*)(PROJ + pj(tok, 5120 + h * 256 + dvh * 128 + ch * 8)); u32x4 w;
; #pragma unroll
;                 for (int e = 0; e < 4; ++e) w[e] = cvt_pk_bf16(bf_lo(v[e]) * z, bf_hi(v[e]) * z);
;                 *(LAS u32x4*)(Vl + row * 272 + ch * 16) = w; }
;     ...
; #pragma unroll
;             for (int ks = 0; ks < 2; ++ks) {
;                 bf16x8 af[4], bfr[4];
;                 LAS unsigned char* vb = Vl + (32 * ks + 8 * g + q4) * 272 + (wr * 64) * 2 + 8 * p4;
;                 LAS unsigned char* kb = Kl + (32 * ks + 8 * g + q4) * 528 + (wc * 64) * 2 + 8 * p4;
; #pragma unroll
;                 for (int a = 0; a < 4; ++a) af[a] = tr_pair(vb + 32 * a, vb + 4 * 272 + 32 * a);
; #pragma unroll
;                 for (int bb = 0; bb < 4; ++bb) bfr[bb] = tr_pair(kb + 32 * bb, kb + 4 * 528 + 32 * bb);
; #pragma unroll
;                 for (int a = 0; a < 4; ++a)
; #pragma unroll
;                     for (int bb = 0; bb < 4; ++bb) acc[a][bb] = MFMA16(af[a], bfr[bb], acc[a][bb]);
	ds_read_b64_tr_b16 v[118:119], v113 offset:34880
	ds_read_b64_tr_b16 v[116:117], v113 offset:33792
	ds_read_b64_tr_b16 v[120:121], v113 offset:33824
	ds_read_b64_tr_b16 v[122:123], v113 offset:34912
	ds_read_b64_tr_b16 v[124:125], v113 offset:33856
	ds_read_b64_tr_b16 v[126:127], v113 offset:34944
	ds_read_b64_tr_b16 v[128:129], v113 offset:33888
	ds_read_b64_tr_b16 v[130:131], v113 offset:34976
	ds_read_b64_tr_b16 v[134:135], v114 offset:2112
	ds_read_b64_tr_b16 v[132:133], v114
	ds_read_b64_tr_b16 v[136:137], v114 offset:32
	ds_read_b64_tr_b16 v[138:139], v114 offset:2144
	ds_read_b64_tr_b16 v[140:141], v114 offset:64
	ds_read_b64_tr_b16 v[142:143], v114 offset:2176
	ds_read_b64_tr_b16 v[144:145], v114 offset:96
	ds_read_b64_tr_b16 v[146:147], v114 offset:2208
	s_waitcnt lgkmcnt(6)
	v_mfma_f32_16x16x32_bf16 v[2:5], v[116:119], v[132:135], v[2:5]
	v_cndmask_b32_e32 v0, v88, v104, vcc
	v_cvt_f32_i32_e32 v0, v0
	v_mul_f32_e32 v0, v94, v0
	s_waitcnt lgkmcnt(4)
	v_mfma_f32_16x16x32_bf16 v[6:9], v[116:119], v[136:139], v[6:9]
	v_mul_f32_e32 v0, 0x3fb8aa3b, v0
	v_exp_f32_e32 v0, v0
	s_waitcnt lgkmcnt(2)
	v_mfma_f32_16x16x32_bf16 v[10:13], v[116:119], v[140:143], v[10:13]
	s_waitcnt lgkmcnt(0)
	v_mfma_f32_16x16x32_bf16 v[14:17], v[116:119], v[144:147], v[14:17]
	v_mfma_f32_16x16x32_bf16 v[116:119], v[124:127], v[132:135], v[34:37]
	v_mfma_f32_16x16x32_bf16 v[18:21], v[120:123], v[132:135], v[18:21]
	v_mfma_f32_16x16x32_bf16 v[22:25], v[120:123], v[136:139], v[22:25]
	v_mfma_f32_16x16x32_bf16 v[26:29], v[120:123], v[140:143], v[26:29]
	v_mfma_f32_16x16x32_bf16 v[30:33], v[120:123], v[144:147], v[30:33]
	v_mfma_f32_16x16x32_bf16 v[120:123], v[124:127], v[136:139], v[38:41]
	v_mfma_f32_16x16x32_bf16 v[148:151], v[124:127], v[140:143], v[42:45]
	v_mfma_f32_16x16x32_bf16 v[124:127], v[124:127], v[144:147], v[46:49]
	v_mfma_f32_16x16x32_bf16 v[132:135], v[128:131], v[132:135], v[50:53]
	v_mfma_f32_16x16x32_bf16 v[136:139], v[128:131], v[136:139], v[54:57]
	v_mfma_f32_16x16x32_bf16 v[140:143], v[128:131], v[140:143], v[58:61]
	v_mfma_f32_16x16x32_bf16 v[128:131], v[128:131], v[144:147], v[62:65]
	ds_read_b64_tr_b16 v[34:35], v113 offset:42496
	ds_read_b64_tr_b16 v[36:37], v113 offset:43584
	ds_read_b64_tr_b16 v[144:145], v113 offset:42528
	ds_read_b64_tr_b16 v[146:147], v113 offset:43616
	ds_read_b64_tr_b16 v[152:153], v113 offset:42560
	ds_read_b64_tr_b16 v[154:155], v113 offset:43648
	ds_read_b64_tr_b16 v[156:157], v113 offset:42592
	ds_read_b64_tr_b16 v[158:159], v113 offset:43680
	ds_read_b64_tr_b16 v[160:161], v114 offset:16896
	ds_read_b64_tr_b16 v[162:163], v114 offset:19008
	ds_read_b64_tr_b16 v[164:165], v114 offset:16928
	ds_read_b64_tr_b16 v[166:167], v114 offset:19040
	ds_read_b64_tr_b16 v[168:169], v114 offset:16960
	ds_read_b64_tr_b16 v[170:171], v114 offset:19072
	ds_read_b64_tr_b16 v[172:173], v114 offset:16992
	ds_read_b64_tr_b16 v[174:175], v114 offset:19104
	s_waitcnt lgkmcnt(0)
	s_barrier
	v_mfma_f32_16x16x32_bf16 v[62:65], v[34:37], v[160:163], v[2:5]
	v_mfma_f32_16x16x32_bf16 v[2:5], v[152:155], v[160:163], v[116:119]
	s_nop 2
	v_lshl_add_u64 v[176:177], s[12:13], 0, v[68:69]
	v_lshlrev_b64 v[176:177], 9, v[176:177]
	v_lshl_add_u64 v[176:177], v[66:67], 0, v[176:177]
	v_add_co_u32_e64 v176, s[0:1], s33, v176
	v_mfma_f32_16x16x32_bf16 v[58:61], v[34:37], v[164:167], v[6:9]
	s_nop 0
	v_addc_co_u32_e64 v177, s[0:1], 0, v177, s[0:1]
	global_load_dwordx4 v[176:179], v[176:177], off
	v_mfma_f32_16x16x32_bf16 v[6:9], v[152:155], v[164:167], v[120:123]
	v_lshl_add_u64 v[180:181], s[12:13], 0, v[70:71]
	v_lshlrev_b64 v[180:181], 9, v[180:181]
	v_lshl_add_u64 v[180:181], v[66:67], 0, v[180:181]
	v_add_co_u32_e64 v180, s[0:1], s33, v180
	s_nop 1
	v_addc_co_u32_e64 v181, s[0:1], 0, v181, s[0:1]
	global_load_dwordx4 v[180:183], v[180:181], off
	v_lshl_add_u64 v[184:185], s[12:13], 0, v[72:73]
	v_lshlrev_b64 v[184:185], 9, v[184:185]
	v_lshl_add_u64 v[184:185], v[66:67], 0, v[184:185]
	v_add_co_u32_e64 v184, s[0:1], s33, v184
	s_nop 1
	v_addc_co_u32_e64 v185, s[0:1], 0, v185, s[0:1]
	global_load_dwordx4 v[184:187], v[184:185], off
	v_lshl_add_u64 v[188:189], s[12:13], 0, v[74:75]
	v_lshlrev_b64 v[188:189], 9, v[188:189]
	v_lshl_add_u64 v[188:189], v[66:67], 0, v[188:189]
	v_add_co_u32_e64 v188, s[0:1], s33, v188
	s_nop 1
	v_addc_co_u32_e64 v189, s[0:1], 0, v189, s[0:1]
	global_load_dwordx4 v[188:191], v[188:189], off
	v_lshl_add_u64 v[192:193], s[6:7], 0, v[88:89]
	v_lshlrev_b64 v[192:193], 9, v[192:193]
	v_lshl_add_u64 v[192:193], v[92:93], 0, v[192:193]
	v_add_co_u32_e64 v192, s[0:1], s33, v192
	s_nop 1
	v_addc_co_u32_e64 v193, s[0:1], 0, v193, s[0:1]
	global_load_dwordx4 v[192:195], v[192:193], off
	s_waitcnt vmcnt(4)
	ds_write_b128 v107, v[176:179]
	s_nop 0
	s_nop 0
	s_nop 0
	s_nop 0
	v_mfma_f32_16x16x32_bf16 v[54:57], v[34:37], v[168:171], v[10:13]
	s_nop 0
	s_nop 0
	s_nop 0
	v_mfma_f32_16x16x32_bf16 v[50:53], v[34:37], v[172:175], v[14:17]
	s_waitcnt vmcnt(3)
	ds_write_b128 v108, v[180:183]
	s_nop 0
	s_nop 0
	s_nop 0
	s_nop 0
	v_mfma_f32_16x16x32_bf16 v[38:41], v[144:147], v[160:163], v[18:21]
	s_nop 0
	s_nop 0
	s_nop 0
	v_mfma_f32_16x16x32_bf16 v[42:45], v[144:147], v[164:167], v[22:25]
	s_waitcnt vmcnt(2)
	ds_write_b128 v109, v[184:187]
	s_nop 0
	s_nop 0
	s_nop 0
	s_nop 0
	v_mfma_f32_16x16x32_bf16 v[46:49], v[144:147], v[168:171], v[26:29]
	s_nop 0
	s_nop 0
	s_nop 0
	v_mfma_f32_16x16x32_bf16 v[34:37], v[144:147], v[172:175], v[30:33]
	s_waitcnt vmcnt(1)
; #define LAS __attribute__((address_space(3)))
; __device__ __forceinline__ unsigned cvt_pk_bf16(float lo, float hi) { const f32x2 v = {lo, hi}; const bf16v2 r = __builtin_convertvector(v, bf16v2); return __builtin_bit_cast(unsigned, r); }
; __device__ __forceinline__ float bf_lo(unsigned u) { return __uint_as_float(u << 16); }
; __device__ __forceinline__ float bf_hi(unsigned u) { return __uint_as_float(u & 0xffff0000u); }
; #define MFMA16(a, b, c) __builtin_amdgcn_mfma_f32_16x16x32_bf16((a), (b), (c), 0, 0, 0)
; __device__ void ret_kv_phase(LAS unsigned char* lds, const bf16_t* PROJ, bf16_t* ST, const float* lgf, const float* lgb) {
;     ...
;             for (int it = 0; it < 2; ++it) { const int idx = tid + 512 * it, row = idx >> 4, ch = idx & 15; const int jl = sub * 64 + row; const size_t tok = (size_t)c * 256 + jl;
;                 const float z = __expf(lg * (float)(dir ? jl : 255 - jl));
;                 const u32x4 v = *(const u32x4*)(PROJ + pj(tok, 5120 + h * 256 + dvh * 128 + ch * 8)); u32x4 w;
; #pragma unroll
;                 for (int e = 0; e < 4; ++e) w[e] = cvt_pk_bf16(bf_lo(v[e]) * z, bf_hi(v[e]) * z);
;                 *(LAS u32x4*)(Vl + row * 272 + ch * 16) = w; }
;             __syncthreads();
; #pragma unroll
;             for (int ks = 0; ks < 2; ++ks) {
;                 bf16x8 af[4], bfr[4];
;                 LAS unsigned char* vb = Vl + (32 * ks + 8 * g + q4) * 272 + (wr * 64) * 2 + 8 * p4;
;                 LAS unsigned char* kb = Kl + (32 * ks + 8 * g + q4) * 528 + (wc * 64) * 2 + 8 * p4;
; #pragma unroll
;                 for (int a = 0; a < 4; ++a) af[a] = tr_pair(vb + 32 * a, vb + 4 * 272 + 32 * a);
; #pragma unroll
;                 for (int bb = 0; bb < 4; ++bb) bfr[bb] = tr_pair(kb + 32 * bb, kb + 4 * 528 + 32 * bb);
; #pragma unroll
;                 for (int a = 0; a < 4; ++a)
; #pragma unroll
;                     for (int bb = 0; bb < 4; ++bb) acc[a][bb] = MFMA16(af[a], bfr[bb], acc[a][bb]);
;             }
	ds_write_b128 v110, v[188:191]
	s_nop 0
	s_nop 0
	s_nop 0
	s_nop 0
	v_mfma_f32_16x16x32_bf16 v[14:17], v[152:155], v[172:175], v[124:127]
	s_nop 0
	s_nop 0
	s_nop 0
	v_mfma_f32_16x16x32_bf16 v[18:21], v[156:159], v[160:163], v[132:135]
	s_add_i32 s0, s4, s17
	s_lshl_b32 s0, s0, 2
	s_or_b32 s0, s0, s16
	v_mfma_f32_16x16x32_bf16 v[22:25], v[156:159], v[164:167], v[136:139]
	s_ashr_i32 s1, s0, 31
	s_lshl_b64 s[0:1], s[0:1], 17
	s_add_u32 s0, s84, s0
	v_mfma_f32_16x16x32_bf16 v[26:29], v[156:159], v[168:171], v[140:143]
	s_addc_u32 s1, s85, s1
	s_add_i32 s14, s14, s10
	s_add_i32 s15, s15, s18
	v_mfma_f32_16x16x32_bf16 v[30:33], v[156:159], v[172:175], v[128:131]
	s_cmpk_gt_i32 s14, 0x5ff
	s_waitcnt vmcnt(0)
	v_lshlrev_b32_e32 v120, 16, v192
	v_and_b32_e32 v121, 0xffff0000, v192
	v_pk_mul_f32 v[120:121], v[0:1], v[120:121] op_sel_hi:[0,1]
	v_cvt_pk_bf16_f32 v192, v120, v121
	v_lshlrev_b32_e32 v120, 16, v193
	v_and_b32_e32 v121, 0xffff0000, v193
	v_pk_mul_f32 v[120:121], v[0:1], v[120:121] op_sel_hi:[0,1]
	v_cvt_pk_bf16_f32 v193, v120, v121
	v_lshlrev_b32_e32 v120, 16, v194
	v_and_b32_e32 v121, 0xffff0000, v194
	v_pk_mul_f32 v[120:121], v[0:1], v[120:121] op_sel_hi:[0,1]
	v_cvt_pk_bf16_f32 v194, v120, v121
	v_lshlrev_b32_e32 v120, 16, v195
	v_and_b32_e32 v121, 0xffff0000, v195
	v_pk_mul_f32 v[120:121], v[0:1], v[120:121] op_sel_hi:[0,1]
	v_cndmask_b32_e32 v0, v90, v105, vcc
	v_cvt_f32_i32_e32 v0, v0
	v_cvt_pk_bf16_f32 v195, v120, v121
	ds_write_b128 v111, v[192:195] offset:33792
	v_mfma_f32_16x16x32_bf16 v[10:13], v[152:155], v[168:171], v[148:151]
	v_mul_f32_e32 v0, v94, v0
	v_lshl_add_u64 v[94:95], s[6:7], 0, v[90:91]
	v_lshlrev_b64 v[94:95], 9, v[94:95]
	v_lshl_add_u64 v[92:93], v[92:93], 0, v[94:95]
	v_add_co_u32_e32 v92, vcc, s33, v92
	v_mul_f32_e32 v0, 0x3fb8aa3b, v0
	s_nop 0
	v_addc_co_u32_e32 v93, vcc, 0, v93, vcc
	global_load_dwordx4 v[92:95], v[92:93], off
	v_exp_f32_e32 v0, v0
	s_waitcnt vmcnt(0)
	v_lshlrev_b32_e32 v116, 16, v92
	v_and_b32_e32 v117, 0xffff0000, v92
	v_pk_mul_f32 v[116:117], v[0:1], v[116:117] op_sel_hi:[0,1]
	v_cvt_pk_bf16_f32 v92, v116, v117
	v_lshlrev_b32_e32 v116, 16, v93
	v_and_b32_e32 v117, 0xffff0000, v93
	v_pk_mul_f32 v[116:117], v[0:1], v[116:117] op_sel_hi:[0,1]
	v_cvt_pk_bf16_f32 v93, v116, v117
	v_lshlrev_b32_e32 v116, 16, v94
	v_and_b32_e32 v117, 0xffff0000, v94
	v_pk_mul_f32 v[116:117], v[0:1], v[116:117] op_sel_hi:[0,1]
	v_cvt_pk_bf16_f32 v94, v116, v117
	v_lshlrev_b32_e32 v116, 16, v95
	v_and_b32_e32 v117, 0xffff0000, v95
	v_pk_mul_f32 v[116:117], v[0:1], v[116:117] op_sel_hi:[0,1]
	v_cvt_pk_bf16_f32 v95, v116, v117
	ds_write_b128 v112, v[92:95] offset:33792
	s_waitcnt lgkmcnt(0)
	s_barrier
	ds_read_b64_tr_b16 v[94:95], v113 offset:34880
	ds_read_b64_tr_b16 v[92:93], v113 offset:33792
	ds_read_b64_tr_b16 v[116:117], v113 offset:33824
	ds_read_b64_tr_b16 v[118:119], v113 offset:34912
	ds_read_b64_tr_b16 v[120:121], v113 offset:33856
	ds_read_b64_tr_b16 v[122:123], v113 offset:34944
	ds_read_b64_tr_b16 v[124:125], v113 offset:33888
	ds_read_b64_tr_b16 v[126:127], v113 offset:34976
	ds_read_b64_tr_b16 v[130:131], v114 offset:2112
	ds_read_b64_tr_b16 v[128:129], v114
	ds_read_b64_tr_b16 v[132:133], v114 offset:32
	ds_read_b64_tr_b16 v[134:135], v114 offset:2144
	ds_read_b64_tr_b16 v[136:137], v114 offset:64
	ds_read_b64_tr_b16 v[138:139], v114 offset:2176
	ds_read_b64_tr_b16 v[140:141], v114 offset:96
	ds_read_b64_tr_b16 v[142:143], v114 offset:2208
	s_waitcnt lgkmcnt(6)
	v_mfma_f32_16x16x32_bf16 v[62:65], v[92:95], v[128:131], v[62:65]
	v_add_u32_e32 v0, s5, v97
	s_waitcnt lgkmcnt(4)
	v_mfma_f32_16x16x32_bf16 v[58:61], v[92:95], v[132:135], v[58:61]
	s_waitcnt lgkmcnt(2)
	v_mfma_f32_16x16x32_bf16 v[54:57], v[92:95], v[136:139], v[54:57]
	s_waitcnt lgkmcnt(0)
	v_mfma_f32_16x16x32_bf16 v[50:53], v[92:95], v[140:143], v[50:53]
	v_mfma_f32_16x16x32_bf16 v[38:41], v[116:119], v[128:131], v[38:41]
	v_mfma_f32_16x16x32_bf16 v[42:45], v[116:119], v[132:135], v[42:45]
	v_mfma_f32_16x16x32_bf16 v[92:95], v[116:119], v[136:139], v[46:49]
	v_mfma_f32_16x16x32_bf16 v[34:37], v[116:119], v[140:143], v[34:37]
	v_mfma_f32_16x16x32_bf16 v[2:5], v[120:123], v[128:131], v[2:5]
	v_mfma_f32_16x16x32_bf16 v[6:9], v[120:123], v[132:135], v[6:9]
	v_mfma_f32_16x16x32_bf16 v[10:13], v[120:123], v[136:139], v[10:13]
	v_mfma_f32_16x16x32_bf16 v[14:17], v[120:123], v[140:143], v[14:17]
	v_mfma_f32_16x16x32_bf16 v[116:119], v[124:127], v[128:131], v[18:21]
	v_mfma_f32_16x16x32_bf16 v[120:123], v[124:127], v[132:135], v[22:25]
	v_mfma_f32_16x16x32_bf16 v[128:131], v[124:127], v[136:139], v[26:29]
	v_mfma_f32_16x16x32_bf16 v[124:127], v[124:127], v[140:143], v[30:33]
	ds_read_b64_tr_b16 v[18:19], v113 offset:42496
	ds_read_b64_tr_b16 v[20:21], v113 offset:43584
	ds_read_b64_tr_b16 v[22:23], v113 offset:42528
	ds_read_b64_tr_b16 v[24:25], v113 offset:43616
	ds_read_b64_tr_b16 v[132:133], v113 offset:42560
	ds_read_b64_tr_b16 v[134:135], v113 offset:43648
	ds_read_b64_tr_b16 v[136:137], v113 offset:42592
	ds_read_b64_tr_b16 v[138:139], v113 offset:43680
	ds_read_b64_tr_b16 v[140:141], v114 offset:16896
	ds_read_b64_tr_b16 v[142:143], v114 offset:19008
	ds_read_b64_tr_b16 v[144:145], v114 offset:16928
	ds_read_b64_tr_b16 v[146:147], v114 offset:19040
	ds_read_b64_tr_b16 v[148:149], v114 offset:16960
	ds_read_b64_tr_b16 v[150:151], v114 offset:19072
	ds_read_b64_tr_b16 v[152:153], v114 offset:16992
	ds_read_b64_tr_b16 v[154:155], v114 offset:19104
	s_waitcnt lgkmcnt(0)
	s_barrier
; __device__ __forceinline__ unsigned cvt_pk_bf16(float lo, float hi) { const f32x2 v = {lo, hi}; const bf16v2 r = __builtin_convertvector(v, bf16v2); return __builtin_bit_cast(unsigned, r); }
; #define MFMA16(a, b, c) __builtin_amdgcn_mfma_f32_16x16x32_bf16((a), (b), (c), 0, 0, 0)
; __device__ void ret_kv_phase(LAS unsigned char* lds, const bf16_t* PROJ, bf16_t* ST, const float* lgf, const float* lgb) {
;     ...
;                 for (int a = 0; a < 4; ++a)
; #pragma unroll
;                     for (int bb = 0; bb < 4; ++bb) acc[a][bb] = MFMA16(af[a], bfr[bb], acc[a][bb]);
;             }
;             __syncthreads();
;         }
;         bf16_t* sp = ST + ((size_t)((dir * 96 + c) * 4 + h)) * 65536;
; #pragma unroll
;         for (int a = 0; a < 4; ++a)
; #pragma unroll
;             for (int j = 0; j < 4; ++j) { const int dv = dvh * 128 + wr * 64 + 16 * a + 4 * g + j;
; #pragma unroll
;                 for (int bb = 0; bb < 4; ++bb) sp[dv * 256 + wc * 64 + 16 * bb + fr] = (bf16_t)(cvt_pk_bf16(acc[a][bb][j], 0.f) & 0xffffu); }
	v_mfma_f32_16x16x32_bf16 v[62:65], v[18:21], v[140:143], v[62:65]
	v_mfma_f32_16x16x32_bf16 v[58:61], v[18:21], v[144:147], v[58:61]
	v_mfma_f32_16x16x32_bf16 v[54:57], v[18:21], v[148:151], v[54:57]
	v_mfma_f32_16x16x32_bf16 v[46:49], v[22:25], v[140:143], v[38:41]
	v_mfma_f32_16x16x32_bf16 v[38:41], v[22:25], v[148:151], v[92:95]
	s_nop 2
	v_lshl_or_b32 v92, v0, 8, v106
	v_mfma_f32_16x16x32_bf16 v[50:53], v[18:21], v[152:155], v[50:53]
	v_ashrrev_i32_e32 v93, 31, v92
	v_cvt_pk_bf16_f32 v0, v62, s0
	v_lshl_add_u64 v[92:93], v[92:93], 1, s[0:1]
	global_store_short v[92:93], v0, off
	v_cvt_pk_bf16_f32 v0, v58, s0
	global_store_short v[92:93], v0, off offset:32
	v_cvt_pk_bf16_f32 v0, v54, s0
	global_store_short v[92:93], v0, off offset:64
	v_cvt_pk_bf16_f32 v0, v50, s0
	global_store_short v[92:93], v0, off offset:96
	v_cvt_pk_bf16_f32 v0, v63, s0
	global_store_short v[92:93], v0, off offset:512
	v_cvt_pk_bf16_f32 v0, v59, s0
	global_store_short v[92:93], v0, off offset:544
	v_cvt_pk_bf16_f32 v0, v55, s0
	global_store_short v[92:93], v0, off offset:576
	v_cvt_pk_bf16_f32 v0, v51, s0
	global_store_short v[92:93], v0, off offset:608
	v_cvt_pk_bf16_f32 v0, v64, s0
	global_store_short v[92:93], v0, off offset:1024
	v_cvt_pk_bf16_f32 v0, v60, s0
	global_store_short v[92:93], v0, off offset:1056
	v_cvt_pk_bf16_f32 v0, v56, s0
	global_store_short v[92:93], v0, off offset:1088
	v_cvt_pk_bf16_f32 v0, v52, s0
	global_store_short v[92:93], v0, off offset:1120
	v_cvt_pk_bf16_f32 v0, v65, s0
	v_mfma_f32_16x16x32_bf16 v[42:45], v[22:25], v[144:147], v[42:45]
	global_store_short v[92:93], v0, off offset:1536
	v_cvt_pk_bf16_f32 v0, v61, s0
	global_store_short v[92:93], v0, off offset:1568
	v_cvt_pk_bf16_f32 v0, v57, s0
	v_mfma_f32_16x16x32_bf16 v[34:37], v[22:25], v[152:155], v[34:37]
	global_store_short v[92:93], v0, off offset:1600
	v_cvt_pk_bf16_f32 v0, v53, s0
	v_add_co_u32_e32 v50, vcc, s22, v92
	global_store_short v[92:93], v0, off offset:1632
	v_cvt_pk_bf16_f32 v0, v46, s0
	v_addc_co_u32_e32 v51, vcc, 0, v93, vcc
	global_store_short v[50:51], v0, off
	v_cvt_pk_bf16_f32 v0, v42, s0
	global_store_short v[50:51], v0, off offset:32
	v_cvt_pk_bf16_f32 v0, v38, s0
	global_store_short v[50:51], v0, off offset:64
	v_cvt_pk_bf16_f32 v0, v34, s0
	global_store_short v[50:51], v0, off offset:96
	v_cvt_pk_bf16_f32 v0, v47, s0
	global_store_short v[50:51], v0, off offset:512
	v_cvt_pk_bf16_f32 v0, v43, s0
	global_store_short v[50:51], v0, off offset:544
	v_cvt_pk_bf16_f32 v0, v39, s0
	global_store_short v[50:51], v0, off offset:576
	v_cvt_pk_bf16_f32 v0, v35, s0
	global_store_short v[50:51], v0, off offset:608
	v_cvt_pk_bf16_f32 v0, v48, s0
	global_store_short v[50:51], v0, off offset:1024
	v_cvt_pk_bf16_f32 v0, v44, s0
	global_store_short v[50:51], v0, off offset:1056
	v_cvt_pk_bf16_f32 v0, v40, s0
	global_store_short v[50:51], v0, off offset:1088
	v_cvt_pk_bf16_f32 v0, v36, s0
	v_mfma_f32_16x16x32_bf16 v[30:33], v[132:135], v[140:143], v[2:5]
	global_store_short v[50:51], v0, off offset:1120
	v_cvt_pk_bf16_f32 v0, v49, s0
	global_store_short v[50:51], v0, off offset:1536
	v_mfma_f32_16x16x32_bf16 v[26:29], v[132:135], v[144:147], v[6:9]
	v_cvt_pk_bf16_f32 v0, v45, s0
	global_store_short v[50:51], v0, off offset:1568
	v_cvt_pk_bf16_f32 v0, v41, s0
	v_mfma_f32_16x16x32_bf16 v[22:25], v[132:135], v[148:151], v[10:13]
	global_store_short v[50:51], v0, off offset:1600
	v_cvt_pk_bf16_f32 v0, v37, s0
	v_add_co_u32_e32 v34, vcc, s23, v92
	v_mfma_f32_16x16x32_bf16 v[18:21], v[132:135], v[152:155], v[14:17]
	global_store_short v[50:51], v0, off offset:1632
	v_cvt_pk_bf16_f32 v0, v30, s0
	v_addc_co_u32_e32 v35, vcc, 0, v93, vcc
	global_store_short v[34:35], v0, off
	v_cvt_pk_bf16_f32 v0, v26, s0
	global_store_short v[34:35], v0, off offset:32
	v_cvt_pk_bf16_f32 v0, v22, s0
	global_store_short v[34:35], v0, off offset:64
	v_cvt_pk_bf16_f32 v0, v18, s0
	global_store_short v[34:35], v0, off offset:96
	v_cvt_pk_bf16_f32 v0, v31, s0
	global_store_short v[34:35], v0, off offset:512
	v_cvt_pk_bf16_f32 v0, v27, s0
	global_store_short v[34:35], v0, off offset:544
	v_cvt_pk_bf16_f32 v0, v23, s0
	global_store_short v[34:35], v0, off offset:576
	v_cvt_pk_bf16_f32 v0, v19, s0
	global_store_short v[34:35], v0, off offset:608
	v_cvt_pk_bf16_f32 v0, v32, s0
	global_store_short v[34:35], v0, off offset:1024
	v_cvt_pk_bf16_f32 v0, v28, s0
	global_store_short v[34:35], v0, off offset:1056
	v_cvt_pk_bf16_f32 v0, v24, s0
	global_store_short v[34:35], v0, off offset:1088
	v_cvt_pk_bf16_f32 v0, v20, s0
	v_mfma_f32_16x16x32_bf16 v[14:17], v[136:139], v[140:143], v[116:119]
	global_store_short v[34:35], v0, off offset:1120
	v_cvt_pk_bf16_f32 v0, v33, s0
	global_store_short v[34:35], v0, off offset:1536
	v_mfma_f32_16x16x32_bf16 v[10:13], v[136:139], v[144:147], v[120:123]
	v_cvt_pk_bf16_f32 v0, v29, s0
	global_store_short v[34:35], v0, off offset:1568
	v_cvt_pk_bf16_f32 v0, v25, s0
	v_mfma_f32_16x16x32_bf16 v[6:9], v[136:139], v[148:151], v[128:131]
	global_store_short v[34:35], v0, off offset:1600
	v_cvt_pk_bf16_f32 v0, v21, s0
	v_add_co_u32_e32 v18, vcc, s24, v92
	v_mfma_f32_16x16x32_bf16 v[2:5], v[136:139], v[152:155], v[124:127]
	global_store_short v[34:35], v0, off offset:1632
	v_cvt_pk_bf16_f32 v0, v14, s0
	v_addc_co_u32_e32 v19, vcc, 0, v93, vcc
	global_store_short v[18:19], v0, off
	v_cvt_pk_bf16_f32 v0, v10, s0
	global_store_short v[18:19], v0, off offset:32
	v_cvt_pk_bf16_f32 v0, v6, s0
	global_store_short v[18:19], v0, off offset:64
	v_cvt_pk_bf16_f32 v0, v2, s0
	global_store_short v[18:19], v0, off offset:96
	v_cvt_pk_bf16_f32 v0, v15, s0
	global_store_short v[18:19], v0, off offset:512
	v_cvt_pk_bf16_f32 v0, v11, s0
	global_store_short v[18:19], v0, off offset:544
	v_cvt_pk_bf16_f32 v0, v7, s0
	global_store_short v[18:19], v0, off offset:576
	v_cvt_pk_bf16_f32 v0, v3, s0
	global_store_short v[18:19], v0, off offset:608
	v_cvt_pk_bf16_f32 v0, v16, s0
	global_store_short v[18:19], v0, off offset:1024
	v_cvt_pk_bf16_f32 v0, v12, s0
	global_store_short v[18:19], v0, off offset:1056
	v_cvt_pk_bf16_f32 v0, v8, s0
	global_store_short v[18:19], v0, off offset:1088
	v_cvt_pk_bf16_f32 v0, v4, s0
	global_store_short v[18:19], v0, off offset:1120
	v_cvt_pk_bf16_f32 v0, v17, s0
	global_store_short v[18:19], v0, off offset:1536
	v_cvt_pk_bf16_f32 v0, v13, s0
	global_store_short v[18:19], v0, off offset:1568
	v_cvt_pk_bf16_f32 v0, v9, s0
	global_store_short v[18:19], v0, off offset:1600
	v_cvt_pk_bf16_f32 v0, v5, s0
	global_store_short v[18:19], v0, off offset:1632
	s_cbranch_scc0 .LBB0_370

; __device__ __forceinline__ unsigned cvt_pk_bf16(float lo, float hi) { const f32x2 v = {lo, hi}; const bf16v2 r = __builtin_convertvector(v, bf16v2); return __builtin_bit_cast(unsigned, r); }
; __device__ void norm_phase(const float* xp, const float* xs, float* out, const float* gain, bf16_t* H, float* SSo) {
;     ...
;     for (int row = gw; row < T; row += nw) {
;         const float* xr = row < 8192 ? xp + (size_t)row * DM : xs + (size_t)(row - 8192) * DM;
;         f32x4 v[8]; float ss = 0.f;
; #pragma unroll
;         for (int j = 0; j < 8; ++j) { v[j] = *(const f32x4*)(xr + (lane + 64 * j) * 4); ss += v[j][0] * v[j][0] + v[j][1] * v[j][1] + v[j][2] * v[j][2] + v[j][3] * v[j][3]; }
; #pragma unroll
;         for (int o = 32; o >= 1; o >>= 1) ss += __shfl_xor(ss, o);
;         if (lane < 8) SSo[(size_t)lane * T + row] = lane == 0 ? ss : 0.f;
; #pragma unroll
;         for (int j = 0; j < 8; ++j) { const f32x4 g = *(const f32x4*)(gain + (lane + 64 * j) * 4);
;             u32x2 w; w.x = cvt_pk_bf16(v[j][0] * g[0], v[j][1] * g[1]); w.y = cvt_pk_bf16(v[j][2] * g[2], v[j][3] * g[3]);
;             *(u32x2*)(H + (size_t)row * DM + (lane + 64 * j) * 4) = w;
;             *(f32x4*)(out + (size_t)row * DM + (lane + 64 * j) * 4) = v[j]; }
;     }
.LBB0_389:
	s_or_b64 exec, exec, s[6:7]
	v_readlane_b32 s6, v254, 28
	v_readlane_b32 s7, v254, 29
	v_lshl_add_u64 v[44:45], v[44:45], 0, s[90:91]
	s_waitcnt vmcnt(0)
	v_pk_mul_f32 v[84:85], v[4:5], v[102:103]
	v_pk_mul_f32 v[82:83], v[2:3], v[100:101]
	v_lshl_add_u64 v[46:47], v[46:47], 0, s[6:7]
	v_cvt_pk_bf16_f32 v82, v82, v83
	v_cvt_pk_bf16_f32 v83, v84, v85
	global_store_dwordx2 v[50:51], v[82:83], off offset:-2048
	global_store_dwordx4 v[48:49], v[2:5], off offset:-4096
	s_movk_i32 s6, 0x5fff
	v_cmp_lt_i32_e64 s[38:39], s6, v44
	v_readlane_b32 s6, v254, 32
	v_readlane_b32 s7, v254, 33
	s_or_b64 s[4:5], s[38:39], s[4:5]
	v_pk_mul_f32 v[88:89], v[8:9], v[106:107]
	v_pk_mul_f32 v[86:87], v[6:7], v[104:105]
	s_nop 0
	v_cvt_pk_bf16_f32 v86, v86, v87
	v_cvt_pk_bf16_f32 v87, v88, v89
	global_store_dwordx2 v[50:51], v[86:87], off offset:-1536
	global_store_dwordx4 v[48:49], v[6:9], off offset:-3072
	v_pk_mul_f32 v[84:85], v[12:13], v[110:111]
	v_pk_mul_f32 v[82:83], v[10:11], v[108:109]
	s_nop 0
	v_cvt_pk_bf16_f32 v82, v82, v83
	v_cvt_pk_bf16_f32 v83, v84, v85
	global_store_dwordx2 v[50:51], v[82:83], off offset:-1024
	global_store_dwordx4 v[48:49], v[10:13], off offset:-2048
	v_pk_mul_f32 v[88:89], v[16:17], v[114:115]
	v_pk_mul_f32 v[86:87], v[14:15], v[112:113]
	s_nop 0
	v_cvt_pk_bf16_f32 v86, v86, v87
	v_cvt_pk_bf16_f32 v87, v88, v89
	global_store_dwordx2 v[50:51], v[86:87], off offset:-512
	global_store_dwordx4 v[48:49], v[14:17], off offset:-1024
	v_pk_mul_f32 v[84:85], v[20:21], v[118:119]
	v_pk_mul_f32 v[82:83], v[18:19], v[116:117]
	s_nop 0
	v_cvt_pk_bf16_f32 v82, v82, v83
	v_cvt_pk_bf16_f32 v83, v84, v85
	global_store_dwordx2 v[50:51], v[82:83], off
	global_store_dwordx4 v[48:49], v[18:21], off
	v_pk_mul_f32 v[88:89], v[24:25], v[122:123]
	v_pk_mul_f32 v[86:87], v[22:23], v[120:121]
	s_nop 0
	v_cvt_pk_bf16_f32 v86, v86, v87
	v_cvt_pk_bf16_f32 v87, v88, v89
	global_store_dwordx2 v[50:51], v[86:87], off offset:512
	global_store_dwordx4 v[48:49], v[22:25], off offset:1024
	v_pk_mul_f32 v[84:85], v[28:29], v[126:127]
	v_pk_mul_f32 v[82:83], v[26:27], v[124:125]
	s_nop 0
	v_cvt_pk_bf16_f32 v82, v82, v83
	v_cvt_pk_bf16_f32 v83, v84, v85
	global_store_dwordx2 v[50:51], v[82:83], off offset:1024
	global_store_dwordx4 v[48:49], v[26:29], off offset:2048
	v_pk_mul_f32 v[88:89], v[32:33], v[130:131]
	v_pk_mul_f32 v[86:87], v[30:31], v[128:129]
	s_nop 0
	v_cvt_pk_bf16_f32 v86, v86, v87
	v_cvt_pk_bf16_f32 v87, v88, v89
	global_store_dwordx2 v[50:51], v[86:87], off offset:1536
	global_store_dwordx4 v[48:49], v[30:33], off offset:3072
	v_lshl_add_u64 v[48:49], v[48:49], 0, s[6:7]
	v_readlane_b32 s6, v254, 43
	v_readlane_b32 s7, v254, 44
	s_nop 1
	v_lshl_add_u64 v[50:51], v[50:51], 0, s[6:7]
	s_andn2_b64 exec, exec, s[4:5]
	s_cbranch_execz .LBB0_393
.LBB0_390:
	v_readlane_b32 s40, v254, 45
	s_movk_i32 s6, 0x2000
	v_readlane_b32 s41, v254, 46
	v_readlane_b32 s43, v254, 48
	v_cmp_gt_i32_e64 s[38:39], s6, v44
	v_add_u32_e32 v2, 0xffffe000, v44
	v_readlane_b32 s42, v254, 47
	v_mov_b32_e32 v4, s43
	v_mov_b32_e32 v5, s41
	v_cndmask_b32_e64 v3, 0, v45, s[38:39]
	v_cndmask_b32_e64 v2, v2, v44, s[38:39]
	v_cndmask_b32_e64 v5, v4, v5, s[38:39]
	v_mov_b32_e32 v4, s42
	v_mov_b32_e32 v6, s40
	v_cndmask_b32_e64 v4, v4, v6, s[38:39]
	v_lshlrev_b64 v[2:3], 13, v[2:3]
	v_lshl_add_u64 v[30:31], v[4:5], 0, v[2:3]
	v_mov_b32_e32 v53, v1
	v_mov_b32_e32 v55, v1
	v_mov_b32_e32 v57, v1
	v_mov_b32_e32 v59, v1
	v_lshl_add_u64 v[70:71], v[30:31], 0, v[0:1]
	v_lshl_add_u64 v[72:73], v[30:31], 0, v[52:53]
	v_lshl_add_u64 v[74:75], v[30:31], 0, v[54:55]
	v_lshl_add_u64 v[76:77], v[30:31], 0, v[56:57]
	v_lshl_add_u64 v[78:79], v[30:31], 0, v[58:59]
	global_load_dwordx4 v[2:5], v[70:71], off
	global_load_dwordx4 v[6:9], v[70:71], off offset:1024
	global_load_dwordx4 v[10:13], v[70:71], off offset:2048
	global_load_dwordx4 v[14:17], v[70:71], off offset:3072
	global_load_dwordx4 v[18:21], v[72:73], off
	global_load_dwordx4 v[22:25], v[74:75], off
	global_load_dwordx4 v[26:29], v[76:77], off
	global_load_dwordx4 v[30:33], v[78:79], off
	global_load_dwordx4 v[100:103], v[34:35], off
	global_load_dwordx4 v[104:107], v[34:35], off offset:1024
	global_load_dwordx4 v[108:111], v[34:35], off offset:2048
	global_load_dwordx4 v[112:115], v[34:35], off offset:3072
	global_load_dwordx4 v[116:119], v[36:37], off
	global_load_dwordx4 v[120:123], v[38:39], off
	global_load_dwordx4 v[124:127], v[40:41], off
	global_load_dwordx4 v[128:131], v[42:43], off
	s_waitcnt lgkmcnt(0)
	v_readlane_b32 s44, v254, 49
	v_readlane_b32 s45, v254, 50
	v_readlane_b32 s46, v254, 51
	v_readlane_b32 s47, v254, 52
	v_readlane_b32 s48, v254, 53
	v_readlane_b32 s49, v254, 54
	v_readlane_b32 s50, v254, 55
	v_readlane_b32 s51, v254, 56
	v_readlane_b32 s52, v254, 57
	v_readlane_b32 s53, v254, 58
	v_readlane_b32 s54, v254, 59
	v_readlane_b32 s55, v254, 60
	s_waitcnt vmcnt(8)
	v_mul_f32_e32 v80, v3, v3
	v_fmac_f32_e32 v80, v2, v2
	v_fmac_f32_e32 v80, v4, v4
	v_fmac_f32_e32 v80, v5, v5
	v_mul_f32_e32 v81, v7, v7
	v_fmac_f32_e32 v81, v6, v6
	v_fmac_f32_e32 v81, v8, v8
	v_fmac_f32_e32 v81, v9, v9
	v_add_f32_e32 v80, v80, v81
	v_mul_f32_e32 v81, v11, v11
	v_fmac_f32_e32 v81, v10, v10
	v_fmac_f32_e32 v81, v12, v12
	v_fmac_f32_e32 v81, v13, v13
	v_add_f32_e32 v80, v80, v81
	v_mul_f32_e32 v81, v15, v15
	v_fmac_f32_e32 v81, v14, v14
	v_fmac_f32_e32 v81, v16, v16
	v_fmac_f32_e32 v81, v17, v17
	v_add_f32_e32 v80, v80, v81
	v_mul_f32_e32 v81, v19, v19
	v_fmac_f32_e32 v81, v18, v18
	v_fmac_f32_e32 v81, v20, v20
	v_fmac_f32_e32 v81, v21, v21
	v_add_f32_e32 v80, v80, v81
	v_mul_f32_e32 v81, v23, v23
	v_fmac_f32_e32 v81, v22, v22
	v_fmac_f32_e32 v81, v24, v24
	v_fmac_f32_e32 v81, v25, v25
	v_add_f32_e32 v80, v80, v81
	v_mul_f32_e32 v81, v27, v27
	v_fmac_f32_e32 v81, v26, v26
	v_fmac_f32_e32 v81, v28, v28
	v_fmac_f32_e32 v81, v29, v29
	v_add_f32_e32 v80, v80, v81
	v_mul_f32_e32 v81, v31, v31
	v_fmac_f32_e32 v81, v30, v30
	v_fmac_f32_e32 v81, v32, v32
	v_fmac_f32_e32 v81, v33, v33
	v_add_f32_e32 v80, v80, v81
	v_mov_b32_e32 v53, v80
	ds_bpermute_b32 v55, v60, v53
	s_waitcnt lgkmcnt(0)
	v_add_f32_e32 v53, v53, v55
	ds_bpermute_b32 v55, v61, v53
	s_waitcnt lgkmcnt(0)
	v_add_f32_e32 v53, v53, v55
	ds_bpermute_b32 v55, v62, v53
	s_waitcnt lgkmcnt(0)
	v_add_f32_e32 v53, v53, v55
	ds_bpermute_b32 v55, v63, v53
	s_waitcnt lgkmcnt(0)
	v_add_f32_e32 v53, v53, v55
	ds_bpermute_b32 v55, v64, v53
	s_waitcnt lgkmcnt(0)
	v_add_f32_e32 v53, v53, v55
	ds_bpermute_b32 v55, v65, v53
	s_and_saveexec_b64 s[6:7], vcc
	s_cbranch_execz .LBB0_389
	s_waitcnt lgkmcnt(0)
	v_add_f32_e32 v53, v53, v55
	v_cndmask_b32_e64 v53, 0, v53, s[0:1]
	global_store_dword v[46:47], v53, off
	s_branch .LBB0_389

; #define LAS __attribute__((address_space(3)))
;     __device__ __forceinline__ void operator()(const f32x4 (&acc)[2][2][4][2], const Unit& u, int wr, int wc, int fr, int fq) const {
;         const int row0 = u.pm * BM + wr * 64 + fr, col0 = u.pn * BM + wc * 32 + 4 * fq;
;         LAS float* part = (LAS float*)(lds + LDS_PART);
;         f32x4 gv[2][2];
;         if (gain) {
; #pragma unroll
;             for (int bj = 0; bj < 2; ++bj)
; #pragma unroll
;                 for (int n = 0; n < 2; ++n) gv[bj][n] = *(const f32x4*)(gain + col0 + bj * HALF + n * 16);
;         }
.LBB0_605:
	s_andn2_b64 vcc, exec, s[0:1]
	s_cbranch_vccnz .LBB0_650
	s_and_b64 vcc, exec, s[74:75]
	s_cbranch_vccnz .Lepi1_fast
	v_lshl_or_b32 v206, s63, 8, v233
	v_cndmask_b32_e64 v0, 0, 1, s[74:75]
	v_cmp_ne_u32_e64 s[44:45], 1, v0
	s_andn2_b64 vcc, exec, s[74:75]
	v_ashrrev_i32_e32 v207, 31, v206
	s_cbranch_vccnz .LBB0_608
	v_lshl_add_u64 v[130:131], v[206:207], 2, s[20:21]
	global_load_dwordx4 v[142:145], v[130:131], off
	global_load_dwordx4 v[138:141], v[130:131], off offset:64
	global_load_dwordx4 v[134:137], v[130:131], off offset:512
	s_nop 0
	global_load_dwordx4 v[130:133], v[130:131], off offset:576

;     __device__ __forceinline__ void operator()(const f32x4 (&acc)[2][2][4][2], const Unit& u, int wr, int wc, int fr, int fq) const {
;     ...
;         if (gain) {
;             asm volatile("s_waitcnt lgkmcnt(0)" ::: "memory"); __builtin_amdgcn_s_barrier(); asm volatile("" ::: "memory");
;             if (wc == 0) { const int lane = fr + 16 * fq;
; #pragma unroll
;                 for (int ai = 0; ai < 2; ++ai) { const int r = ai * HALF + wr * 64 + lane; const float s = (part[r] + part[256 + r]) + (part[512 + r] + part[768 + r]);
;                     SSo[(size_t)u.pn * T + u.pm * BM + r] = s; } }
;         }
.Lepi1_join:
	s_waitcnt lgkmcnt(0)
	s_barrier
	v_readlane_b32 s0, v255, 48
	v_readlane_b32 s1, v255, 49
	s_andn2_b64 vcc, exec, s[0:1]
	s_cbranch_vccnz .LBB0_648
	ds_read2st64_b32 v[130:131], v236 offset1:4
	s_ashr_i32 s49, s48, 31
	s_mul_i32 s1, s63, 0x18000
	v_readlane_b32 s12, v255, 45
	s_mul_hi_i32 s0, s63, 0x18000
	s_waitcnt lgkmcnt(0)
	v_add_f32_e32 v0, v130, v131
	ds_read2st64_b32 v[130:131], v236 offset0:8 offset1:12
	v_readlane_b32 s13, v255, 46
	s_add_u32 s12, s12, s1
	ds_read2st64_b32 v[132:133], v237 offset1:4
	s_addc_u32 s13, s13, s0
	s_lshl_b64 s[0:1], s[48:49], 2
	s_add_u32 s0, s12, s0
	s_addc_u32 s1, s13, s1
	s_waitcnt lgkmcnt(1)
	v_add_f32_e32 v130, v130, v131
	v_add_f32_e32 v0, v0, v130
	v_lshl_add_u64 v[130:131], v[196:197], 2, s[0:1]
	global_store_dword v[130:131], v0, off
	s_waitcnt lgkmcnt(0)
	v_add_f32_e32 v0, v132, v133
	ds_read2st64_b32 v[132:133], v237 offset0:8 offset1:12
	s_waitcnt lgkmcnt(0)
	v_add_f32_e32 v132, v132, v133
	v_add_f32_e32 v0, v0, v132
	global_store_dword v[130:131], v0, off offset:512

; #define LAS __attribute__((address_space(3)))
; __device__ __forceinline__ unsigned cvt_pk_bf16(float lo, float hi) { const f32x2 v = {lo, hi}; const bf16v2 r = __builtin_convertvector(v, bf16v2); return __builtin_bit_cast(unsigned, r); }
;     __device__ __forceinline__ void operator()(const f32x4 (&acc)[2][2][4][2], const Unit& u, int wr, int wc, int fr, int fq) const {
;         const int row0 = u.pm * BM + wr * 64 + fr, col0 = u.pn * BM + wc * 32 + 4 * fq;
;         LAS float* part = (LAS float*)(lds + LDS_PART);
;         f32x4 gv[2][2];
;         if (gain) {
; #pragma unroll
;             for (int bj = 0; bj < 2; ++bj)
; #pragma unroll
;                 for (int n = 0; n < 2; ++n) gv[bj][n] = *(const f32x4*)(gain + col0 + bj * HALF + n * 16);
;         }
; #pragma unroll
;         for (int aim = 0; aim < 4; ++aim) { const int ai = aim >> 1;
;             f32x4 res[4][2][2];
; #pragma unroll
;             for (int m = (aim & 1) * 2; m < (aim & 1) * 2 + 2; ++m)
; #pragma unroll
;                 for (int bj = 0; bj < 2; ++bj)
; #pragma unroll
;                     for (int n = 0; n < 2; ++n) res[m][bj][n] = *(const f32x4*)(C + (size_t)(row0 + ai * HALF + m * 16) * ldc + col0 + bj * HALF + n * 16);
; #pragma unroll
;             for (int m = (aim & 1) * 2; m < (aim & 1) * 2 + 2; ++m) { const int row = row0 + ai * HALF + m * 16; float* rowp = C + (size_t)row * ldc + col0; float sq = 0.f;
; #pragma unroll
;                 for (int bj = 0; bj < 2; ++bj)
; #pragma unroll
;                     for (int n = 0; n < 2; ++n) { f32x4* p = (f32x4*)(rowp + bj * HALF + n * 16); const f32x4 x = res[m][bj][n] + acc[ai][bj][m][n] * scale; *p = x;
;                         if (gain) { sq += x[0] * x[0] + x[1] * x[1] + x[2] * x[2] + x[3] * x[3]; const f32x4 y = x * gv[bj][n];
;                             u32x2 w; w.x = cvt_pk_bf16(y[0], y[1]); w.y = cvt_pk_bf16(y[2], y[3]); *(u32x2*)(XG + (size_t)row * ldc + col0 + bj * HALF + n * 16) = w; } }
;                 if (gain) { sq += __shfl_xor(sq, 16); sq += __shfl_xor(sq, 32); if (fq == 0) part[wc * 256 + ai * HALF + wr * 64 + m * 16 + fr] = sq; } }
.Lepi1_fast:
	v_lshl_or_b32 v206, s63, 8, v233
	v_add_u32_e32 v0, s48, v235
	v_lshlrev_b32_e32 v178, 13, v0
	v_lshl_add_u32 v178, v206, 2, v178
	v_lshlrev_b32_e32 v0, 2, v206
	v_lshrrev_b32_e32 v179, 1, v178
	global_load_dwordx4 v[130:133], v0, s[20:21] offset:0
	global_load_dwordx4 v[134:137], v0, s[20:21] offset:64
	global_load_dwordx4 v[138:141], v0, s[20:21] offset:512
	global_load_dwordx4 v[142:145], v0, s[20:21] offset:576
	s_add_u32 s0, s4, 0x0
	s_addc_u32 s1, s5, 0
	global_load_dwordx4 v[146:149], v178, s[0:1] offset:0
	global_load_dwordx4 v[150:153], v178, s[0:1] offset:64
	global_load_dwordx4 v[154:157], v178, s[0:1] offset:512
	global_load_dwordx4 v[158:161], v178, s[0:1] offset:576
	s_add_u32 s0, s4, 0x20000
	s_addc_u32 s1, s5, 0
	global_load_dwordx4 v[162:165], v178, s[0:1] offset:0
	global_load_dwordx4 v[166:169], v178, s[0:1] offset:64
	global_load_dwordx4 v[170:173], v178, s[0:1] offset:512
	global_load_dwordx4 v[174:177], v178, s[0:1] offset:576
	s_add_u32 s0, s4, 0x40000
	s_addc_u32 s1, s5, 0
	global_load_dwordx4 v[206:209], v178, s[0:1] offset:0
	global_load_dwordx4 v[210:213], v178, s[0:1] offset:64
	global_load_dwordx4 v[214:217], v178, s[0:1] offset:512
	global_load_dwordx4 v[218:221], v178, s[0:1] offset:576
	v_xor_b32_e32 v180, 16, v229
	v_xor_b32_e32 v181, 32, v229
	v_lshlrev_b32_e32 v180, 2, v180
	v_lshlrev_b32_e32 v181, 2, v181
	s_waitcnt vmcnt(8)
	v_pk_fma_f32 v[126:127], s[22:23], v[126:127], v[146:147]
	v_pk_fma_f32 v[128:129], s[22:23], v[128:129], v[148:149]
	v_pk_fma_f32 v[122:123], s[22:23], v[122:123], v[150:151]
	v_pk_fma_f32 v[124:125], s[22:23], v[124:125], v[152:153]
	v_pk_fma_f32 v[94:95], s[22:23], v[94:95], v[154:155]
	v_pk_fma_f32 v[96:97], s[22:23], v[96:97], v[156:157]
	v_pk_fma_f32 v[90:91], s[22:23], v[90:91], v[158:159]
	v_pk_fma_f32 v[92:93], s[22:23], v[92:93], v[160:161]
	s_add_u32 s0, s4, 0x60000
	s_addc_u32 s1, s5, 0
	global_load_dwordx4 v[146:149], v178, s[0:1] offset:0
	global_load_dwordx4 v[150:153], v178, s[0:1] offset:64
	global_load_dwordx4 v[154:157], v178, s[0:1] offset:512
	global_load_dwordx4 v[158:161], v178, s[0:1] offset:576
	s_add_u32 s0, s4, 0x0
	s_addc_u32 s1, s5, 0
	s_add_u32 s12, s14, 0x0
	s_addc_u32 s13, s15, 0
	global_store_dwordx4 v178, v[126:129], s[0:1] offset:0
	global_store_dwordx4 v178, v[122:125], s[0:1] offset:64
	global_store_dwordx4 v178, v[94:97], s[0:1] offset:512
	global_store_dwordx4 v178, v[90:93], s[0:1] offset:576
	v_pk_mul_f32 v[222:223], v[130:131], v[126:127]
	v_pk_mul_f32 v[224:225], v[132:133], v[128:129]
	v_cvt_pk_bf16_f32 v182, v222, v223
	v_cvt_pk_bf16_f32 v183, v224, v225
	global_store_dwordx2 v179, v[182:183], s[12:13] offset:0
	v_pk_mul_f32 v[222:223], v[134:135], v[122:123]
	v_pk_mul_f32 v[224:225], v[136:137], v[124:125]
	v_cvt_pk_bf16_f32 v184, v222, v223
	v_cvt_pk_bf16_f32 v185, v224, v225
	global_store_dwordx2 v179, v[184:185], s[12:13] offset:32
	v_pk_mul_f32 v[222:223], v[138:139], v[94:95]
	v_pk_mul_f32 v[224:225], v[140:141], v[96:97]
	v_cvt_pk_bf16_f32 v182, v222, v223
	v_cvt_pk_bf16_f32 v183, v224, v225
	global_store_dwordx2 v179, v[182:183], s[12:13] offset:256
	v_pk_mul_f32 v[222:223], v[142:143], v[90:91]
	v_pk_mul_f32 v[224:225], v[144:145], v[92:93]
	v_cvt_pk_bf16_f32 v184, v222, v223
	v_cvt_pk_bf16_f32 v185, v224, v225
	global_store_dwordx2 v179, v[184:185], s[12:13] offset:288
	v_mul_f32_e32 v186, v126, v126
	v_fmac_f32_e32 v186, v127, v127
	v_fmac_f32_e32 v186, v128, v128
	v_fmac_f32_e32 v186, v129, v129
	v_fmac_f32_e32 v186, v122, v122
	v_fmac_f32_e32 v186, v123, v123
	v_fmac_f32_e32 v186, v124, v124
	v_fmac_f32_e32 v186, v125, v125
	v_fmac_f32_e32 v186, v94, v94
	v_fmac_f32_e32 v186, v95, v95
	v_fmac_f32_e32 v186, v96, v96
	v_fmac_f32_e32 v186, v97, v97
	v_fmac_f32_e32 v186, v90, v90
	v_fmac_f32_e32 v186, v91, v91
	v_fmac_f32_e32 v186, v92, v92
	v_fmac_f32_e32 v186, v93, v93
	ds_bpermute_b32 v187, v180, v186
	s_waitcnt lgkmcnt(0)
	v_add_f32_e32 v186, v186, v187
	ds_bpermute_b32 v187, v181, v186
	s_waitcnt lgkmcnt(0)
	v_add_f32_e32 v186, v186, v187
	s_and_saveexec_b64 s[44:45], s[38:39]
	ds_write_b32 v231, v186 offset:0
	s_or_b64 exec, exec, s[44:45]
	s_waitcnt vmcnt(16)
	v_pk_fma_f32 v[118:119], s[22:23], v[118:119], v[162:163]
	v_pk_fma_f32 v[120:121], s[22:23], v[120:121], v[164:165]
	v_pk_fma_f32 v[114:115], s[22:23], v[114:115], v[166:167]
	v_pk_fma_f32 v[116:117], s[22:23], v[116:117], v[168:169]
	v_pk_fma_f32 v[86:87], s[22:23], v[86:87], v[170:171]
	v_pk_fma_f32 v[88:89], s[22:23], v[88:89], v[172:173]
	v_pk_fma_f32 v[82:83], s[22:23], v[82:83], v[174:175]
	v_pk_fma_f32 v[84:85], s[22:23], v[84:85], v[176:177]
	s_add_u32 s0, s4, 0x100000
	s_addc_u32 s1, s5, 0
	global_load_dwordx4 v[162:165], v178, s[0:1] offset:0
	global_load_dwordx4 v[166:169], v178, s[0:1] offset:64
	global_load_dwordx4 v[170:173], v178, s[0:1] offset:512
	global_load_dwordx4 v[174:177], v178, s[0:1] offset:576
	s_add_u32 s0, s4, 0x20000
	s_addc_u32 s1, s5, 0
	s_add_u32 s12, s14, 0x10000
	s_addc_u32 s13, s15, 0
	global_store_dwordx4 v178, v[118:121], s[0:1] offset:0
	global_store_dwordx4 v178, v[114:117], s[0:1] offset:64
	global_store_dwordx4 v178, v[86:89], s[0:1] offset:512
	global_store_dwordx4 v178, v[82:85], s[0:1] offset:576
	v_pk_mul_f32 v[222:223], v[130:131], v[118:119]
	v_pk_mul_f32 v[224:225], v[132:133], v[120:121]
	v_cvt_pk_bf16_f32 v182, v222, v223
	v_cvt_pk_bf16_f32 v183, v224, v225
	global_store_dwordx2 v179, v[182:183], s[12:13] offset:0
	v_pk_mul_f32 v[222:223], v[134:135], v[114:115]
	v_pk_mul_f32 v[224:225], v[136:137], v[116:117]
	v_cvt_pk_bf16_f32 v184, v222, v223
	v_cvt_pk_bf16_f32 v185, v224, v225
	global_store_dwordx2 v179, v[184:185], s[12:13] offset:32
	v_pk_mul_f32 v[222:223], v[138:139], v[86:87]
	v_pk_mul_f32 v[224:225], v[140:141], v[88:89]
	v_cvt_pk_bf16_f32 v182, v222, v223
	v_cvt_pk_bf16_f32 v183, v224, v225
	global_store_dwordx2 v179, v[182:183], s[12:13] offset:256
	v_pk_mul_f32 v[222:223], v[142:143], v[82:83]
	v_pk_mul_f32 v[224:225], v[144:145], v[84:85]
	v_cvt_pk_bf16_f32 v184, v222, v223
	v_cvt_pk_bf16_f32 v185, v224, v225
	global_store_dwordx2 v179, v[184:185], s[12:13] offset:288
	v_mul_f32_e32 v186, v118, v118
	v_fmac_f32_e32 v186, v119, v119
	v_fmac_f32_e32 v186, v120, v120
	v_fmac_f32_e32 v186, v121, v121
	v_fmac_f32_e32 v186, v114, v114
	v_fmac_f32_e32 v186, v115, v115
	v_fmac_f32_e32 v186, v116, v116
	v_fmac_f32_e32 v186, v117, v117
	v_fmac_f32_e32 v186, v86, v86
	v_fmac_f32_e32 v186, v87, v87
	v_fmac_f32_e32 v186, v88, v88
	v_fmac_f32_e32 v186, v89, v89
	v_fmac_f32_e32 v186, v82, v82
	v_fmac_f32_e32 v186, v83, v83
	v_fmac_f32_e32 v186, v84, v84
	v_fmac_f32_e32 v186, v85, v85
	ds_bpermute_b32 v187, v180, v186
	s_waitcnt lgkmcnt(0)
; __device__ __forceinline__ unsigned cvt_pk_bf16(float lo, float hi) { const f32x2 v = {lo, hi}; const bf16v2 r = __builtin_convertvector(v, bf16v2); return __builtin_bit_cast(unsigned, r); }
;     __device__ __forceinline__ void operator()(const f32x4 (&acc)[2][2][4][2], const Unit& u, int wr, int wc, int fr, int fq) const {
;     ...
;                 for (int bj = 0; bj < 2; ++bj)
; #pragma unroll
;                     for (int n = 0; n < 2; ++n) res[m][bj][n] = *(const f32x4*)(C + (size_t)(row0 + ai * HALF + m * 16) * ldc + col0 + bj * HALF + n * 16);
; #pragma unroll
;             for (int m = (aim & 1) * 2; m < (aim & 1) * 2 + 2; ++m) { const int row = row0 + ai * HALF + m * 16; float* rowp = C + (size_t)row * ldc + col0; float sq = 0.f;
; #pragma unroll
;                 for (int bj = 0; bj < 2; ++bj)
; #pragma unroll
;                     for (int n = 0; n < 2; ++n) { f32x4* p = (f32x4*)(rowp + bj * HALF + n * 16); const f32x4 x = res[m][bj][n] + acc[ai][bj][m][n] * scale; *p = x;
;                         if (gain) { sq += x[0] * x[0] + x[1] * x[1] + x[2] * x[2] + x[3] * x[3]; const f32x4 y = x * gv[bj][n];
;                             u32x2 w; w.x = cvt_pk_bf16(y[0], y[1]); w.y = cvt_pk_bf16(y[2], y[3]); *(u32x2*)(XG + (size_t)row * ldc + col0 + bj * HALF + n * 16) = w; } }
;                 if (gain) { sq += __shfl_xor(sq, 16); sq += __shfl_xor(sq, 32); if (fq == 0) part[wc * 256 + ai * HALF + wr * 64 + m * 16 + fr] = sq; } }
	v_add_f32_e32 v186, v186, v187
	ds_bpermute_b32 v187, v181, v186
	s_waitcnt lgkmcnt(0)
	v_add_f32_e32 v186, v186, v187
	s_and_saveexec_b64 s[44:45], s[38:39]
	ds_write_b32 v231, v186 offset:64
	s_or_b64 exec, exec, s[44:45]
	s_waitcnt vmcnt(24)
	v_pk_fma_f32 v[110:111], s[22:23], v[110:111], v[206:207]
	v_pk_fma_f32 v[112:113], s[22:23], v[112:113], v[208:209]
	v_pk_fma_f32 v[106:107], s[22:23], v[106:107], v[210:211]
	v_pk_fma_f32 v[108:109], s[22:23], v[108:109], v[212:213]
	v_pk_fma_f32 v[78:79], s[22:23], v[78:79], v[214:215]
	v_pk_fma_f32 v[80:81], s[22:23], v[80:81], v[216:217]
	v_pk_fma_f32 v[74:75], s[22:23], v[74:75], v[218:219]
	v_pk_fma_f32 v[76:77], s[22:23], v[76:77], v[220:221]
	s_add_u32 s0, s4, 0x120000
	s_addc_u32 s1, s5, 0
	global_load_dwordx4 v[206:209], v178, s[0:1] offset:0
	global_load_dwordx4 v[210:213], v178, s[0:1] offset:64
	global_load_dwordx4 v[214:217], v178, s[0:1] offset:512
	global_load_dwordx4 v[218:221], v178, s[0:1] offset:576
	s_add_u32 s0, s4, 0x40000
	s_addc_u32 s1, s5, 0
	s_add_u32 s12, s14, 0x20000
	s_addc_u32 s13, s15, 0
	global_store_dwordx4 v178, v[110:113], s[0:1] offset:0
	global_store_dwordx4 v178, v[106:109], s[0:1] offset:64
	global_store_dwordx4 v178, v[78:81], s[0:1] offset:512
	global_store_dwordx4 v178, v[74:77], s[0:1] offset:576
	v_pk_mul_f32 v[222:223], v[130:131], v[110:111]
	v_pk_mul_f32 v[224:225], v[132:133], v[112:113]
	v_cvt_pk_bf16_f32 v182, v222, v223
	v_cvt_pk_bf16_f32 v183, v224, v225
	global_store_dwordx2 v179, v[182:183], s[12:13] offset:0
	v_pk_mul_f32 v[222:223], v[134:135], v[106:107]
	v_pk_mul_f32 v[224:225], v[136:137], v[108:109]
	v_cvt_pk_bf16_f32 v184, v222, v223
	v_cvt_pk_bf16_f32 v185, v224, v225
	global_store_dwordx2 v179, v[184:185], s[12:13] offset:32
	v_pk_mul_f32 v[222:223], v[138:139], v[78:79]
	v_pk_mul_f32 v[224:225], v[140:141], v[80:81]
	v_cvt_pk_bf16_f32 v182, v222, v223
	v_cvt_pk_bf16_f32 v183, v224, v225
	global_store_dwordx2 v179, v[182:183], s[12:13] offset:256
	v_pk_mul_f32 v[222:223], v[142:143], v[74:75]
	v_pk_mul_f32 v[224:225], v[144:145], v[76:77]
	v_cvt_pk_bf16_f32 v184, v222, v223
	v_cvt_pk_bf16_f32 v185, v224, v225
	global_store_dwordx2 v179, v[184:185], s[12:13] offset:288
	v_mul_f32_e32 v186, v110, v110
	v_fmac_f32_e32 v186, v111, v111
	v_fmac_f32_e32 v186, v112, v112
	v_fmac_f32_e32 v186, v113, v113
	v_fmac_f32_e32 v186, v106, v106
	v_fmac_f32_e32 v186, v107, v107
	v_fmac_f32_e32 v186, v108, v108
	v_fmac_f32_e32 v186, v109, v109
	v_fmac_f32_e32 v186, v78, v78
	v_fmac_f32_e32 v186, v79, v79
	v_fmac_f32_e32 v186, v80, v80
	v_fmac_f32_e32 v186, v81, v81
	v_fmac_f32_e32 v186, v74, v74
	v_fmac_f32_e32 v186, v75, v75
	v_fmac_f32_e32 v186, v76, v76
	v_fmac_f32_e32 v186, v77, v77
	ds_bpermute_b32 v187, v180, v186
	s_waitcnt lgkmcnt(0)
	v_add_f32_e32 v186, v186, v187
	ds_bpermute_b32 v187, v181, v186
	s_waitcnt lgkmcnt(0)
	v_add_f32_e32 v186, v186, v187
	s_and_saveexec_b64 s[44:45], s[38:39]
	ds_write_b32 v231, v186 offset:128
	s_or_b64 exec, exec, s[44:45]
	s_waitcnt vmcnt(32)
	v_pk_fma_f32 v[102:103], s[22:23], v[102:103], v[146:147]
	v_pk_fma_f32 v[104:105], s[22:23], v[104:105], v[148:149]
	v_pk_fma_f32 v[98:99], s[22:23], v[98:99], v[150:151]
	v_pk_fma_f32 v[100:101], s[22:23], v[100:101], v[152:153]
	v_pk_fma_f32 v[70:71], s[22:23], v[70:71], v[154:155]
	v_pk_fma_f32 v[72:73], s[22:23], v[72:73], v[156:157]
	v_pk_fma_f32 v[66:67], s[22:23], v[66:67], v[158:159]
	v_pk_fma_f32 v[68:69], s[22:23], v[68:69], v[160:161]
	s_add_u32 s0, s4, 0x140000
	s_addc_u32 s1, s5, 0
	global_load_dwordx4 v[146:149], v178, s[0:1] offset:0
	global_load_dwordx4 v[150:153], v178, s[0:1] offset:64
	global_load_dwordx4 v[154:157], v178, s[0:1] offset:512
	global_load_dwordx4 v[158:161], v178, s[0:1] offset:576
	s_add_u32 s0, s4, 0x60000
	s_addc_u32 s1, s5, 0
	s_add_u32 s12, s14, 0x30000
	s_addc_u32 s13, s15, 0
	global_store_dwordx4 v178, v[102:105], s[0:1] offset:0
	global_store_dwordx4 v178, v[98:101], s[0:1] offset:64
	global_store_dwordx4 v178, v[70:73], s[0:1] offset:512
	global_store_dwordx4 v178, v[66:69], s[0:1] offset:576
	v_pk_mul_f32 v[222:223], v[130:131], v[102:103]
	v_pk_mul_f32 v[224:225], v[132:133], v[104:105]
	v_cvt_pk_bf16_f32 v182, v222, v223
	v_cvt_pk_bf16_f32 v183, v224, v225
	global_store_dwordx2 v179, v[182:183], s[12:13] offset:0
	v_pk_mul_f32 v[222:223], v[134:135], v[98:99]
	v_pk_mul_f32 v[224:225], v[136:137], v[100:101]
	v_cvt_pk_bf16_f32 v184, v222, v223
	v_cvt_pk_bf16_f32 v185, v224, v225
	global_store_dwordx2 v179, v[184:185], s[12:13] offset:32
	v_pk_mul_f32 v[222:223], v[138:139], v[70:71]
	v_pk_mul_f32 v[224:225], v[140:141], v[72:73]
	v_cvt_pk_bf16_f32 v182, v222, v223
	v_cvt_pk_bf16_f32 v183, v224, v225
	global_store_dwordx2 v179, v[182:183], s[12:13] offset:256
	v_pk_mul_f32 v[222:223], v[142:143], v[66:67]
	v_pk_mul_f32 v[224:225], v[144:145], v[68:69]
	v_cvt_pk_bf16_f32 v184, v222, v223
	v_cvt_pk_bf16_f32 v185, v224, v225
	global_store_dwordx2 v179, v[184:185], s[12:13] offset:288
	v_mul_f32_e32 v186, v102, v102
	v_fmac_f32_e32 v186, v103, v103
	v_fmac_f32_e32 v186, v104, v104
	v_fmac_f32_e32 v186, v105, v105
	v_fmac_f32_e32 v186, v98, v98
	v_fmac_f32_e32 v186, v99, v99
	v_fmac_f32_e32 v186, v100, v100
	v_fmac_f32_e32 v186, v101, v101
	v_fmac_f32_e32 v186, v70, v70
	v_fmac_f32_e32 v186, v71, v71
	v_fmac_f32_e32 v186, v72, v72
	v_fmac_f32_e32 v186, v73, v73
	v_fmac_f32_e32 v186, v66, v66
	v_fmac_f32_e32 v186, v67, v67
	v_fmac_f32_e32 v186, v68, v68
	v_fmac_f32_e32 v186, v69, v69
	ds_bpermute_b32 v187, v180, v186
	s_waitcnt lgkmcnt(0)
	v_add_f32_e32 v186, v186, v187
	ds_bpermute_b32 v187, v181, v186
	s_waitcnt lgkmcnt(0)
; __device__ __forceinline__ unsigned cvt_pk_bf16(float lo, float hi) { const f32x2 v = {lo, hi}; const bf16v2 r = __builtin_convertvector(v, bf16v2); return __builtin_bit_cast(unsigned, r); }
;     __device__ __forceinline__ void operator()(const f32x4 (&acc)[2][2][4][2], const Unit& u, int wr, int wc, int fr, int fq) const {
;     ...
;                 for (int bj = 0; bj < 2; ++bj)
; #pragma unroll
;                     for (int n = 0; n < 2; ++n) res[m][bj][n] = *(const f32x4*)(C + (size_t)(row0 + ai * HALF + m * 16) * ldc + col0 + bj * HALF + n * 16);
; #pragma unroll
;             for (int m = (aim & 1) * 2; m < (aim & 1) * 2 + 2; ++m) { const int row = row0 + ai * HALF + m * 16; float* rowp = C + (size_t)row * ldc + col0; float sq = 0.f;
; #pragma unroll
;                 for (int bj = 0; bj < 2; ++bj)
; #pragma unroll
;                     for (int n = 0; n < 2; ++n) { f32x4* p = (f32x4*)(rowp + bj * HALF + n * 16); const f32x4 x = res[m][bj][n] + acc[ai][bj][m][n] * scale; *p = x;
;                         if (gain) { sq += x[0] * x[0] + x[1] * x[1] + x[2] * x[2] + x[3] * x[3]; const f32x4 y = x * gv[bj][n];
;                             u32x2 w; w.x = cvt_pk_bf16(y[0], y[1]); w.y = cvt_pk_bf16(y[2], y[3]); *(u32x2*)(XG + (size_t)row * ldc + col0 + bj * HALF + n * 16) = w; } }
;                 if (gain) { sq += __shfl_xor(sq, 16); sq += __shfl_xor(sq, 32); if (fq == 0) part[wc * 256 + ai * HALF + wr * 64 + m * 16 + fr] = sq; } }
	v_add_f32_e32 v186, v186, v187
	s_and_saveexec_b64 s[44:45], s[38:39]
	ds_write_b32 v231, v186 offset:192
	s_or_b64 exec, exec, s[44:45]
	s_waitcnt vmcnt(32)
	v_pk_fma_f32 v[62:63], s[22:23], v[62:63], v[162:163]
	v_pk_fma_f32 v[64:65], s[22:23], v[64:65], v[164:165]
	v_pk_fma_f32 v[58:59], s[22:23], v[58:59], v[166:167]
	v_pk_fma_f32 v[60:61], s[22:23], v[60:61], v[168:169]
	v_pk_fma_f32 v[30:31], s[22:23], v[30:31], v[170:171]
	v_pk_fma_f32 v[32:33], s[22:23], v[32:33], v[172:173]
	v_pk_fma_f32 v[26:27], s[22:23], v[26:27], v[174:175]
	v_pk_fma_f32 v[28:29], s[22:23], v[28:29], v[176:177]
	s_add_u32 s0, s4, 0x160000
	s_addc_u32 s1, s5, 0
	global_load_dwordx4 v[162:165], v178, s[0:1] offset:0
	global_load_dwordx4 v[166:169], v178, s[0:1] offset:64
	global_load_dwordx4 v[170:173], v178, s[0:1] offset:512
	global_load_dwordx4 v[174:177], v178, s[0:1] offset:576
	s_add_u32 s0, s4, 0x100000
	s_addc_u32 s1, s5, 0
	s_add_u32 s12, s14, 0x80000
	s_addc_u32 s13, s15, 0
	global_store_dwordx4 v178, v[62:65], s[0:1] offset:0
	global_store_dwordx4 v178, v[58:61], s[0:1] offset:64
	global_store_dwordx4 v178, v[30:33], s[0:1] offset:512
	global_store_dwordx4 v178, v[26:29], s[0:1] offset:576
	v_pk_mul_f32 v[222:223], v[130:131], v[62:63]
	v_pk_mul_f32 v[224:225], v[132:133], v[64:65]
	v_cvt_pk_bf16_f32 v182, v222, v223
	v_cvt_pk_bf16_f32 v183, v224, v225
	global_store_dwordx2 v179, v[182:183], s[12:13] offset:0
	v_pk_mul_f32 v[222:223], v[134:135], v[58:59]
	v_pk_mul_f32 v[224:225], v[136:137], v[60:61]
	v_cvt_pk_bf16_f32 v184, v222, v223
	v_cvt_pk_bf16_f32 v185, v224, v225
	global_store_dwordx2 v179, v[184:185], s[12:13] offset:32
	v_pk_mul_f32 v[222:223], v[138:139], v[30:31]
	v_pk_mul_f32 v[224:225], v[140:141], v[32:33]
	v_cvt_pk_bf16_f32 v182, v222, v223
	v_cvt_pk_bf16_f32 v183, v224, v225
	global_store_dwordx2 v179, v[182:183], s[12:13] offset:256
	v_pk_mul_f32 v[222:223], v[142:143], v[26:27]
	v_pk_mul_f32 v[224:225], v[144:145], v[28:29]
	v_cvt_pk_bf16_f32 v184, v222, v223
	v_cvt_pk_bf16_f32 v185, v224, v225
	global_store_dwordx2 v179, v[184:185], s[12:13] offset:288
	v_mul_f32_e32 v186, v62, v62
	v_fmac_f32_e32 v186, v63, v63
	v_fmac_f32_e32 v186, v64, v64
	v_fmac_f32_e32 v186, v65, v65
	v_fmac_f32_e32 v186, v58, v58
	v_fmac_f32_e32 v186, v59, v59
	v_fmac_f32_e32 v186, v60, v60
	v_fmac_f32_e32 v186, v61, v61
	v_fmac_f32_e32 v186, v30, v30
	v_fmac_f32_e32 v186, v31, v31
	v_fmac_f32_e32 v186, v32, v32
	v_fmac_f32_e32 v186, v33, v33
	v_fmac_f32_e32 v186, v26, v26
	v_fmac_f32_e32 v186, v27, v27
	v_fmac_f32_e32 v186, v28, v28
	v_fmac_f32_e32 v186, v29, v29
	ds_bpermute_b32 v187, v180, v186
	s_waitcnt lgkmcnt(0)
	v_add_f32_e32 v186, v186, v187
	ds_bpermute_b32 v187, v181, v186
	s_waitcnt lgkmcnt(0)
	v_add_f32_e32 v186, v186, v187
	s_and_saveexec_b64 s[44:45], s[38:39]
	ds_write_b32 v231, v186 offset:512
	s_or_b64 exec, exec, s[44:45]
	s_waitcnt vmcnt(32)
	v_pk_fma_f32 v[54:55], s[22:23], v[54:55], v[206:207]
	v_pk_fma_f32 v[56:57], s[22:23], v[56:57], v[208:209]
	v_pk_fma_f32 v[50:51], s[22:23], v[50:51], v[210:211]
	v_pk_fma_f32 v[52:53], s[22:23], v[52:53], v[212:213]
	v_pk_fma_f32 v[22:23], s[22:23], v[22:23], v[214:215]
	v_pk_fma_f32 v[24:25], s[22:23], v[24:25], v[216:217]
	v_pk_fma_f32 v[18:19], s[22:23], v[18:19], v[218:219]
	v_pk_fma_f32 v[20:21], s[22:23], v[20:21], v[220:221]
	s_add_u32 s0, s4, 0x120000
	s_addc_u32 s1, s5, 0
	s_add_u32 s12, s14, 0x90000
	s_addc_u32 s13, s15, 0
	global_store_dwordx4 v178, v[54:57], s[0:1] offset:0
	global_store_dwordx4 v178, v[50:53], s[0:1] offset:64
	global_store_dwordx4 v178, v[22:25], s[0:1] offset:512
	global_store_dwordx4 v178, v[18:21], s[0:1] offset:576
	v_pk_mul_f32 v[222:223], v[130:131], v[54:55]
	v_pk_mul_f32 v[224:225], v[132:133], v[56:57]
	v_cvt_pk_bf16_f32 v182, v222, v223
	v_cvt_pk_bf16_f32 v183, v224, v225
	global_store_dwordx2 v179, v[182:183], s[12:13] offset:0
	v_pk_mul_f32 v[222:223], v[134:135], v[50:51]
	v_pk_mul_f32 v[224:225], v[136:137], v[52:53]
	v_cvt_pk_bf16_f32 v184, v222, v223
	v_cvt_pk_bf16_f32 v185, v224, v225
	global_store_dwordx2 v179, v[184:185], s[12:13] offset:32
	v_pk_mul_f32 v[222:223], v[138:139], v[22:23]
	v_pk_mul_f32 v[224:225], v[140:141], v[24:25]
	v_cvt_pk_bf16_f32 v182, v222, v223
	v_cvt_pk_bf16_f32 v183, v224, v225
	global_store_dwordx2 v179, v[182:183], s[12:13] offset:256
	v_pk_mul_f32 v[222:223], v[142:143], v[18:19]
	v_pk_mul_f32 v[224:225], v[144:145], v[20:21]
	v_cvt_pk_bf16_f32 v184, v222, v223
	v_cvt_pk_bf16_f32 v185, v224, v225
	global_store_dwordx2 v179, v[184:185], s[12:13] offset:288
	v_mul_f32_e32 v186, v54, v54
	v_fmac_f32_e32 v186, v55, v55
	v_fmac_f32_e32 v186, v56, v56
	v_fmac_f32_e32 v186, v57, v57
	v_fmac_f32_e32 v186, v50, v50
	v_fmac_f32_e32 v186, v51, v51
	v_fmac_f32_e32 v186, v52, v52
	v_fmac_f32_e32 v186, v53, v53
	v_fmac_f32_e32 v186, v22, v22
	v_fmac_f32_e32 v186, v23, v23
	v_fmac_f32_e32 v186, v24, v24
	v_fmac_f32_e32 v186, v25, v25
	v_fmac_f32_e32 v186, v18, v18
	v_fmac_f32_e32 v186, v19, v19
	v_fmac_f32_e32 v186, v20, v20
	v_fmac_f32_e32 v186, v21, v21
	ds_bpermute_b32 v187, v180, v186
	s_waitcnt lgkmcnt(0)
; __device__ __forceinline__ unsigned cvt_pk_bf16(float lo, float hi) { const f32x2 v = {lo, hi}; const bf16v2 r = __builtin_convertvector(v, bf16v2); return __builtin_bit_cast(unsigned, r); }
;     __device__ __forceinline__ void operator()(const f32x4 (&acc)[2][2][4][2], const Unit& u, int wr, int wc, int fr, int fq) const {
;     ...
;                 for (int bj = 0; bj < 2; ++bj)
; #pragma unroll
;                     for (int n = 0; n < 2; ++n) res[m][bj][n] = *(const f32x4*)(C + (size_t)(row0 + ai * HALF + m * 16) * ldc + col0 + bj * HALF + n * 16);
; #pragma unroll
;             for (int m = (aim & 1) * 2; m < (aim & 1) * 2 + 2; ++m) { const int row = row0 + ai * HALF + m * 16; float* rowp = C + (size_t)row * ldc + col0; float sq = 0.f;
; #pragma unroll
;                 for (int bj = 0; bj < 2; ++bj)
; #pragma unroll
;                     for (int n = 0; n < 2; ++n) { f32x4* p = (f32x4*)(rowp + bj * HALF + n * 16); const f32x4 x = res[m][bj][n] + acc[ai][bj][m][n] * scale; *p = x;
;                         if (gain) { sq += x[0] * x[0] + x[1] * x[1] + x[2] * x[2] + x[3] * x[3]; const f32x4 y = x * gv[bj][n];
;                             u32x2 w; w.x = cvt_pk_bf16(y[0], y[1]); w.y = cvt_pk_bf16(y[2], y[3]); *(u32x2*)(XG + (size_t)row * ldc + col0 + bj * HALF + n * 16) = w; } }
;                 if (gain) { sq += __shfl_xor(sq, 16); sq += __shfl_xor(sq, 32); if (fq == 0) part[wc * 256 + ai * HALF + wr * 64 + m * 16 + fr] = sq; } }
	v_add_f32_e32 v186, v186, v187
	ds_bpermute_b32 v187, v181, v186
	s_waitcnt lgkmcnt(0)
	v_add_f32_e32 v186, v186, v187
	s_and_saveexec_b64 s[44:45], s[38:39]
	ds_write_b32 v231, v186 offset:576
	s_or_b64 exec, exec, s[44:45]
	s_waitcnt vmcnt(28)
	v_pk_fma_f32 v[46:47], s[22:23], v[46:47], v[146:147]
	v_pk_fma_f32 v[48:49], s[22:23], v[48:49], v[148:149]
	v_pk_fma_f32 v[42:43], s[22:23], v[42:43], v[150:151]
	v_pk_fma_f32 v[44:45], s[22:23], v[44:45], v[152:153]
	v_pk_fma_f32 v[14:15], s[22:23], v[14:15], v[154:155]
	v_pk_fma_f32 v[16:17], s[22:23], v[16:17], v[156:157]
	v_pk_fma_f32 v[10:11], s[22:23], v[10:11], v[158:159]
	v_pk_fma_f32 v[12:13], s[22:23], v[12:13], v[160:161]
	s_add_u32 s0, s4, 0x140000
	s_addc_u32 s1, s5, 0
	s_add_u32 s12, s14, 0xa0000
	s_addc_u32 s13, s15, 0
	global_store_dwordx4 v178, v[46:49], s[0:1] offset:0
	global_store_dwordx4 v178, v[42:45], s[0:1] offset:64
	global_store_dwordx4 v178, v[14:17], s[0:1] offset:512
	global_store_dwordx4 v178, v[10:13], s[0:1] offset:576
	v_pk_mul_f32 v[222:223], v[130:131], v[46:47]
	v_pk_mul_f32 v[224:225], v[132:133], v[48:49]
	v_cvt_pk_bf16_f32 v182, v222, v223
	v_cvt_pk_bf16_f32 v183, v224, v225
	global_store_dwordx2 v179, v[182:183], s[12:13] offset:0
	v_pk_mul_f32 v[222:223], v[134:135], v[42:43]
	v_pk_mul_f32 v[224:225], v[136:137], v[44:45]
	v_cvt_pk_bf16_f32 v184, v222, v223
	v_cvt_pk_bf16_f32 v185, v224, v225
	global_store_dwordx2 v179, v[184:185], s[12:13] offset:32
	v_pk_mul_f32 v[222:223], v[138:139], v[14:15]
	v_pk_mul_f32 v[224:225], v[140:141], v[16:17]
	v_cvt_pk_bf16_f32 v182, v222, v223
	v_cvt_pk_bf16_f32 v183, v224, v225
	global_store_dwordx2 v179, v[182:183], s[12:13] offset:256
	v_pk_mul_f32 v[222:223], v[142:143], v[10:11]
	v_pk_mul_f32 v[224:225], v[144:145], v[12:13]
	v_cvt_pk_bf16_f32 v184, v222, v223
	v_cvt_pk_bf16_f32 v185, v224, v225
	global_store_dwordx2 v179, v[184:185], s[12:13] offset:288
	v_mul_f32_e32 v186, v46, v46
	v_fmac_f32_e32 v186, v47, v47
	v_fmac_f32_e32 v186, v48, v48
	v_fmac_f32_e32 v186, v49, v49
	v_fmac_f32_e32 v186, v42, v42
	v_fmac_f32_e32 v186, v43, v43
	v_fmac_f32_e32 v186, v44, v44
	v_fmac_f32_e32 v186, v45, v45
	v_fmac_f32_e32 v186, v14, v14
	v_fmac_f32_e32 v186, v15, v15
	v_fmac_f32_e32 v186, v16, v16
	v_fmac_f32_e32 v186, v17, v17
	v_fmac_f32_e32 v186, v10, v10
	v_fmac_f32_e32 v186, v11, v11
	v_fmac_f32_e32 v186, v12, v12
	v_fmac_f32_e32 v186, v13, v13
	ds_bpermute_b32 v187, v180, v186
	s_waitcnt lgkmcnt(0)
	v_add_f32_e32 v186, v186, v187
	ds_bpermute_b32 v187, v181, v186
	s_waitcnt lgkmcnt(0)
	v_add_f32_e32 v186, v186, v187
	s_and_saveexec_b64 s[44:45], s[38:39]
	ds_write_b32 v231, v186 offset:640
	s_or_b64 exec, exec, s[44:45]
	s_waitcnt vmcnt(24)
	v_pk_fma_f32 v[38:39], s[22:23], v[38:39], v[162:163]
	v_pk_fma_f32 v[40:41], s[22:23], v[40:41], v[164:165]
	v_pk_fma_f32 v[34:35], s[22:23], v[34:35], v[166:167]
	v_pk_fma_f32 v[36:37], s[22:23], v[36:37], v[168:169]
	v_pk_fma_f32 v[6:7], s[22:23], v[6:7], v[170:171]
	v_pk_fma_f32 v[8:9], s[22:23], v[8:9], v[172:173]
	v_pk_fma_f32 v[2:3], s[22:23], v[2:3], v[174:175]
	v_pk_fma_f32 v[4:5], s[22:23], v[4:5], v[176:177]
	s_add_u32 s0, s4, 0x160000
	s_addc_u32 s1, s5, 0
	s_add_u32 s12, s14, 0xb0000
	s_addc_u32 s13, s15, 0
	global_store_dwordx4 v178, v[38:41], s[0:1] offset:0
	global_store_dwordx4 v178, v[34:37], s[0:1] offset:64
	global_store_dwordx4 v178, v[6:9], s[0:1] offset:512
	global_store_dwordx4 v178, v[2:5], s[0:1] offset:576
	v_pk_mul_f32 v[222:223], v[130:131], v[38:39]
	v_pk_mul_f32 v[224:225], v[132:133], v[40:41]
	v_cvt_pk_bf16_f32 v182, v222, v223
	v_cvt_pk_bf16_f32 v183, v224, v225
	global_store_dwordx2 v179, v[182:183], s[12:13] offset:0
	v_pk_mul_f32 v[222:223], v[134:135], v[34:35]
	v_pk_mul_f32 v[224:225], v[136:137], v[36:37]
	v_cvt_pk_bf16_f32 v184, v222, v223
	v_cvt_pk_bf16_f32 v185, v224, v225
	global_store_dwordx2 v179, v[184:185], s[12:13] offset:32
	v_pk_mul_f32 v[222:223], v[138:139], v[6:7]
	v_pk_mul_f32 v[224:225], v[140:141], v[8:9]
	v_cvt_pk_bf16_f32 v182, v222, v223
	v_cvt_pk_bf16_f32 v183, v224, v225
	global_store_dwordx2 v179, v[182:183], s[12:13] offset:256
	v_pk_mul_f32 v[222:223], v[142:143], v[2:3]
	v_pk_mul_f32 v[224:225], v[144:145], v[4:5]
	v_cvt_pk_bf16_f32 v184, v222, v223
	v_cvt_pk_bf16_f32 v185, v224, v225
	global_store_dwordx2 v179, v[184:185], s[12:13] offset:288
	v_mul_f32_e32 v186, v38, v38
	v_fmac_f32_e32 v186, v39, v39
	v_fmac_f32_e32 v186, v40, v40
	v_fmac_f32_e32 v186, v41, v41
	v_fmac_f32_e32 v186, v34, v34
	v_fmac_f32_e32 v186, v35, v35
	v_fmac_f32_e32 v186, v36, v36
	v_fmac_f32_e32 v186, v37, v37
	v_fmac_f32_e32 v186, v6, v6
	v_fmac_f32_e32 v186, v7, v7
	v_fmac_f32_e32 v186, v8, v8
	v_fmac_f32_e32 v186, v9, v9
	v_fmac_f32_e32 v186, v2, v2
	v_fmac_f32_e32 v186, v3, v3
	v_fmac_f32_e32 v186, v4, v4
	v_fmac_f32_e32 v186, v5, v5
	ds_bpermute_b32 v187, v180, v186
	s_waitcnt lgkmcnt(0)
	v_add_f32_e32 v186, v186, v187
	ds_bpermute_b32 v187, v181, v186
	s_waitcnt lgkmcnt(0)
	v_add_f32_e32 v186, v186, v187
	s_and_saveexec_b64 s[44:45], s[38:39]
	ds_write_b32 v231, v186 offset:704
	s_or_b64 exec, exec, s[44:45]
	s_branch .Lepi1_join
